# resid-loop gain vectors preloaded, barrier non-leaders poll top generation word, pooled-window loads batched; natural code placement
# speedup vs baseline: 1.0081x; 1.0081x over previous
; __device__ __forceinline__ unsigned pk2(float lo, float hi) { unsigned r; asm("v_cvt_pk_bf16_f32 %0, %1, %2" : "=v"(r) : "v"(lo), "v"(hi)); return r; }
; __device__ __forceinline__ void row_norm_store(const f32x4 (&v)[8], const float* gain, bf16_t* orow, int lane) {
;     float s = 0.f;
; #pragma unroll
;     for (int j = 0; j < 8; ++j) s += (v[j][0] * v[j][0] + v[j][1] * v[j][1]) + (v[j][2] * v[j][2] + v[j][3] * v[j][3]);
;     const float rs = 1.0f / sqrtf(wave_sum(s) * (1.0f / D_MODEL) + EPS);
; #pragma unroll
;     for (int j = 0; j < 8; ++j) { const f32x4 gv = *(const f32x4*)(gain + 4 * lane + 256 * j); const f32x4 y = v[j] * rs * gv;
;         u32x2 w; w.x = pk2(y[0], y[1]); w.y = pk2(y[2], y[3]); *(u32x2*)(orow + 4 * lane + 256 * j) = w; }
; }
; __device__ __forceinline__ void p_prologue(const Args& a, LAS unsigned char* lds, const Ctx& c) {
;     ...
;     for (int m = c.gw; m < MTOK; m += c.NGW) { f32x4 v[8];
; #pragma unroll
;         for (int j = 0; j < 8; ++j) v[j] = *(const f32x4*)(a.x + (size_t)m * D_MODEL + 4 * c.lane + 256 * j);
;         row_norm_store(v, a.gains, HN0 + (size_t)m * LDH, c.lane); }
.LBB0_71:
	s_or_b64 exec, exec, s[2:3]
	s_cmpk_gt_i32 s34, 0x3fff
	s_cbranch_scc1 .LBB0_74
	v_mbcnt_lo_u32_b32 v1, -1, 0
	v_mbcnt_hi_u32_b32 v2, -1, v1
	v_and_b32_e32 v1, 64, v2
	v_add_u32_e32 v3, 64, v1
	v_xor_b32_e32 v1, 1, v2
	v_cmp_lt_i32_e32 vcc, v1, v3
	v_xor_b32_e32 v4, 2, v2
	v_readlane_b32 s8, v236, 2
	v_cndmask_b32_e32 v1, v2, v1, vcc
	v_cmp_lt_i32_e32 vcc, v4, v3
	v_readlane_b32 s10, v236, 4
	v_readlane_b32 s11, v236, 5
	v_cndmask_b32_e32 v4, v2, v4, vcc
	v_lshlrev_b32_e32 v40, 2, v4
	v_xor_b32_e32 v4, 4, v2
	v_cmp_lt_i32_e32 vcc, v4, v3
	s_mov_b64 s[2:3], 0x1400
	s_ashr_i32 s35, s34, 31
	v_cndmask_b32_e32 v4, v2, v4, vcc
	v_lshlrev_b32_e32 v41, 2, v4
	v_xor_b32_e32 v4, 8, v2
	v_cmp_lt_i32_e32 vcc, v4, v3
	v_readlane_b32 s9, v236, 3
	s_mov_b64 s[0:1], 0x1000
	v_cndmask_b32_e32 v4, v2, v4, vcc
	v_lshlrev_b32_e32 v42, 2, v4
	v_xor_b32_e32 v4, 16, v2
	v_cmp_lt_i32_e32 vcc, v4, v3
	v_lshlrev_b32_e32 v1, 2, v1
	v_mov_b32_e32 v45, 0x358637bd
	v_cndmask_b32_e32 v4, v2, v4, vcc
	v_lshlrev_b32_e32 v43, 2, v4
	v_xor_b32_e32 v4, 32, v2
	v_cmp_lt_i32_e32 vcc, v4, v3
	v_mov_b32_e32 v3, 0
	s_mov_b32 s6, 0xf800000
	v_cndmask_b32_e32 v2, v2, v4, vcc
	v_lshlrev_b32_e32 v44, 2, v2
	v_lshlrev_b32_e32 v2, 4, v164
	v_lshl_add_u64 v[26:27], s[10:11], 0, v[2:3]
	v_lshl_add_u64 v[30:31], v[26:27], 0, s[2:3]
	s_mov_b64 s[2:3], 0x1800
	v_lshl_add_u64 v[32:33], v[26:27], 0, s[2:3]
	s_mov_b64 s[2:3], 0x1c00
	v_lshl_add_u64 v[34:35], v[26:27], 0, s[2:3]
	s_lshl_b64 s[2:3], s[34:35], 13
	s_add_u32 s2, s8, s2
	s_addc_u32 s3, s9, s3
	v_lshl_add_u64 v[4:5], s[2:3], 0, v[2:3]
	s_ashr_i32 s61, s60, 31
	v_lshl_add_u64 v[28:29], v[26:27], 0, s[0:1]
	v_lshl_add_u64 v[36:37], v[4:5], 0, s[0:1]
	s_lshl_b64 s[2:3], s[60:61], 13
	v_readlane_b32 s0, v236, 19
	s_add_u32 s0, s94, s0
	v_lshlrev_b32_e32 v2, 3, v164
	s_addc_u32 s1, s95, s81
	v_lshl_add_u64 v[38:39], s[0:1], 0, v[2:3]
	v_mov_b32_e32 v46, 0x260
	s_mov_b32 s7, s34
	v_readlane_b32 s12, v236, 6
	v_readlane_b32 s13, v236, 7
	v_readlane_b32 s14, v236, 8
	v_readlane_b32 s15, v236, 9
	v_readlane_b32 s16, v236, 10
	v_readlane_b32 s17, v236, 11
	v_readlane_b32 s18, v236, 12
	v_readlane_b32 s19, v236, 13
	v_readlane_b32 s20, v236, 14
	v_readlane_b32 s21, v236, 15
	v_readlane_b32 s22, v236, 16
	v_readlane_b32 s23, v236, 17
	global_load_dwordx4 v[176:179], v[26:27], off offset:1024
	global_load_dwordx4 v[180:183], v[26:27], off offset:2048
	global_load_dwordx4 v[184:187], v[26:27], off offset:3072
	global_load_dwordx4 v[188:191], v[28:29], off
	global_load_dwordx4 v[192:195], v[30:31], off
	global_load_dwordx4 v[196:199], v[32:33], off
	global_load_dwordx4 v[200:203], v[34:35], off
; __device__ __forceinline__ unsigned pk2(float lo, float hi) { unsigned r; asm("v_cvt_pk_bf16_f32 %0, %1, %2" : "=v"(r) : "v"(lo), "v"(hi)); return r; }
; __device__ __forceinline__ void row_norm_store(const f32x4 (&v)[8], const float* gain, bf16_t* orow, int lane) {
;     float s = 0.f;
; #pragma unroll
;     for (int j = 0; j < 8; ++j) s += (v[j][0] * v[j][0] + v[j][1] * v[j][1]) + (v[j][2] * v[j][2] + v[j][3] * v[j][3]);
;     const float rs = 1.0f / sqrtf(wave_sum(s) * (1.0f / D_MODEL) + EPS);
; #pragma unroll
;     for (int j = 0; j < 8; ++j) { const f32x4 gv = *(const f32x4*)(gain + 4 * lane + 256 * j); const f32x4 y = v[j] * rs * gv;
;         u32x2 w; w.x = pk2(y[0], y[1]); w.y = pk2(y[2], y[3]); *(u32x2*)(orow + 4 * lane + 256 * j) = w; }
; }
; __device__ __forceinline__ void p_prologue(const Args& a, LAS unsigned char* lds, const Ctx& c) {
;     ...
;     for (int m = c.gw; m < MTOK; m += c.NGW) { f32x4 v[8];
; #pragma unroll
;         for (int j = 0; j < 8; ++j) v[j] = *(const f32x4*)(a.x + (size_t)m * D_MODEL + 4 * c.lane + 256 * j);
;         row_norm_store(v, a.gains, HN0 + (size_t)m * LDH, c.lane); }
.LBB0_73:
	global_load_dwordx4 v[48:51], v[36:37], off offset:-4096
	global_load_dwordx4 v[52:55], v[36:37], off offset:-3072
	global_load_dwordx4 v[22:25], v[36:37], off offset:-2048
	global_load_dwordx4 v[18:21], v[36:37], off offset:-1024
	global_load_dwordx4 v[10:13], v[36:37], off offset:1024
	global_load_dwordx4 v[6:9], v[36:37], off offset:2048
	global_load_dwordx4 v[14:17], v[36:37], off
	global_load_dwordx4 v[2:5], v[36:37], off offset:3072
	global_load_dwordx4 v[56:59], v[26:27], off
	s_add_i32 s7, s7, s60
	v_lshl_add_u64 v[36:37], v[36:37], 0, s[2:3]
	s_cmpk_lt_i32 s7, 0x4000
	s_waitcnt vmcnt(8)
	v_mov_b32_e32 v62, v49
	s_waitcnt vmcnt(7)
	v_mov_b32_e32 v63, v53
	v_mov_b32_e32 v66, v51
	v_mov_b32_e32 v67, v55
	v_mov_b32_e32 v60, v48
	v_mov_b32_e32 v61, v52
	v_mov_b32_e32 v64, v50
	v_mov_b32_e32 v65, v54
	s_waitcnt vmcnt(6)
	v_pk_mul_f32 v[68:69], v[24:25], v[24:25]
	v_pk_mul_f32 v[70:71], v[22:23], v[22:23]
	v_pk_mul_f32 v[62:63], v[62:63], v[62:63]
	v_pk_mul_f32 v[66:67], v[66:67], v[66:67]
	v_pk_mov_b32 v[84:85], v[70:71], v[68:69] op_sel:[1,0]
	v_mov_b32_e32 v71, v69
	v_pk_fma_f32 v[60:61], v[60:61], v[60:61], v[62:63]
	v_pk_fma_f32 v[62:63], v[64:65], v[64:65], v[66:67]
	s_waitcnt vmcnt(5)
	v_mul_f32_e32 v72, v18, v18
	v_mul_f32_e32 v74, v20, v20
	v_pk_add_f32 v[64:65], v[84:85], v[70:71]
	v_pk_add_f32 v[60:61], v[60:61], v[62:63]
	v_pk_fma_f32 v[68:69], v[18:19], v[18:19], v[72:73] op_sel_hi:[1,1,0]
	v_pk_fma_f32 v[72:73], v[20:21], v[20:21], v[74:75] op_sel_hi:[1,1,0]
	v_pk_add_f32 v[62:63], v[64:65], v[64:65] op_sel_hi:[0,1]
	v_pk_add_f32 v[60:61], v[60:61], v[60:61] op_sel_hi:[0,1]
	s_waitcnt vmcnt(4)
	v_pk_mul_f32 v[76:77], v[12:13], v[12:13]
	v_pk_mul_f32 v[78:79], v[10:11], v[10:11]
	s_waitcnt vmcnt(2)
	v_mul_f32_e32 v68, v14, v14
	v_mul_f32_e32 v72, v15, v15
	v_mul_f32_e32 v62, v16, v16
	v_mul_f32_e32 v60, v17, v17
	v_pk_mov_b32 v[74:75], v[78:79], v[76:77] op_sel:[1,0]
	v_mov_b32_e32 v79, v77
	v_pk_add_f32 v[64:65], v[68:69], v[72:73]
	v_pk_add_f32 v[60:61], v[62:63], v[60:61]
	v_mul_f32_e32 v80, v6, v6
	v_mul_f32_e32 v82, v8, v8
	v_pk_add_f32 v[66:67], v[74:75], v[78:79]
	v_pk_add_f32 v[60:61], v[64:65], v[60:61]
	v_pk_fma_f32 v[76:77], v[6:7], v[6:7], v[80:81] op_sel_hi:[1,1,0]
	v_pk_fma_f32 v[80:81], v[8:9], v[8:9], v[82:83] op_sel_hi:[1,1,0]
	v_pk_add_f32 v[66:67], v[66:67], v[66:67] op_sel_hi:[0,1]
	v_pk_add_f32 v[60:61], v[60:61], v[60:61] op_sel_hi:[0,1]
	s_waitcnt vmcnt(1)
	v_mul_f32_e32 v76, v2, v2
	v_mul_f32_e32 v80, v3, v3
	v_mul_f32_e32 v66, v4, v4
	v_mul_f32_e32 v60, v5, v5
	v_pk_add_f32 v[68:69], v[76:77], v[80:81]
	v_pk_add_f32 v[60:61], v[66:67], v[60:61]
	s_nop 0
	v_pk_add_f32 v[60:61], v[68:69], v[60:61]
	s_nop 0
	v_add_f32_e32 v47, v60, v61
	ds_bpermute_b32 v60, v1, v47
	s_waitcnt lgkmcnt(0)
	v_add_f32_e32 v47, v47, v60
	ds_bpermute_b32 v60, v40, v47
	s_waitcnt lgkmcnt(0)
	v_add_f32_e32 v47, v47, v60
	ds_bpermute_b32 v60, v41, v47
	s_waitcnt lgkmcnt(0)
	v_add_f32_e32 v47, v47, v60
	ds_bpermute_b32 v60, v42, v47
	s_waitcnt lgkmcnt(0)
	v_add_f32_e32 v47, v47, v60
	ds_bpermute_b32 v60, v43, v47
	s_waitcnt lgkmcnt(0)
	v_add_f32_e32 v47, v47, v60
	ds_bpermute_b32 v60, v44, v47
	s_waitcnt lgkmcnt(0)
	v_add_f32_e32 v47, v47, v60
	v_fmamk_f32 v47, v47, 0x3a000000, v45
	v_mul_f32_e32 v60, 0x4f800000, v47
	v_cmp_gt_f32_e32 vcc, s6, v47
	s_nop 1
	v_cndmask_b32_e32 v47, v47, v60, vcc
	v_sqrt_f32_e32 v60, v47
	s_nop 0
	v_add_u32_e32 v61, -1, v60
	v_add_u32_e32 v62, 1, v60
	v_fma_f32 v63, -v61, v60, v47
	v_fma_f32 v64, -v62, v60, v47
	v_cmp_ge_f32_e64 s[0:1], 0, v63
	s_nop 1
	v_cndmask_b32_e64 v60, v60, v61, s[0:1]
	v_cmp_lt_f32_e64 s[0:1], 0, v64
	s_nop 1
	v_cndmask_b32_e64 v60, v60, v62, s[0:1]
	v_mul_f32_e32 v61, 0x37800000, v60
	v_cndmask_b32_e32 v60, v60, v61, vcc
	v_cmp_class_f32_e32 vcc, v47, v46
	s_nop 1
	v_cndmask_b32_e32 v47, v60, v47, vcc
	v_div_scale_f32 v60, s[0:1], v47, v47, 1.0
	v_rcp_f32_e32 v62, v60
	v_div_scale_f32 v61, vcc, 1.0, v47, 1.0
	v_fma_f32 v63, -v60, v62, 1.0
	v_fmac_f32_e32 v62, v63, v62
	v_mul_f32_e32 v63, v61, v62
	v_fma_f32 v64, -v60, v63, v61
	v_fmac_f32_e32 v63, v64, v62
	v_fma_f32 v60, -v60, v63, v61
	v_div_fmas_f32 v60, v60, v62, v63
	v_div_fixup_f32 v60, v60, v47, 1.0
	v_pk_mul_f32 v[48:49], v[48:49], v[60:61] op_sel_hi:[1,0]
	v_pk_mul_f32 v[50:51], v[50:51], v[60:61] op_sel_hi:[1,0]
	s_waitcnt vmcnt(0)
	v_pk_mul_f32 v[48:49], v[56:57], v[48:49]
	v_pk_mul_f32 v[50:51], v[58:59], v[50:51]
	v_cvt_pk_bf16_f32 v48, v48, v49
	v_pk_mul_f32 v[52:53], v[52:53], v[60:61] op_sel_hi:[1,0]
	v_cvt_pk_bf16_f32 v49, v50, v51
	global_store_dwordx2 v[38:39], v[48:49], off
	v_pk_mul_f32 v[54:55], v[54:55], v[60:61] op_sel_hi:[1,0]
	v_pk_mul_f32 v[22:23], v[22:23], v[60:61] op_sel_hi:[1,0]
	v_pk_mul_f32 v[24:25], v[24:25], v[60:61] op_sel_hi:[1,0]
	v_pk_mul_f32 v[18:19], v[18:19], v[60:61] op_sel_hi:[1,0]
	v_pk_mul_f32 v[20:21], v[20:21], v[60:61] op_sel_hi:[1,0]
	v_pk_mul_f32 v[14:15], v[14:15], v[60:61] op_sel_hi:[1,0]
	v_pk_mul_f32 v[16:17], v[16:17], v[60:61] op_sel_hi:[1,0]
	v_pk_mul_f32 v[10:11], v[10:11], v[60:61] op_sel_hi:[1,0]
	v_pk_mul_f32 v[12:13], v[12:13], v[60:61] op_sel_hi:[1,0]
	v_pk_mul_f32 v[6:7], v[6:7], v[60:61] op_sel_hi:[1,0]
	v_pk_mul_f32 v[8:9], v[8:9], v[60:61] op_sel_hi:[1,0]
	v_pk_mul_f32 v[2:3], v[2:3], v[60:61] op_sel_hi:[1,0]
	v_pk_mul_f32 v[4:5], v[4:5], v[60:61] op_sel_hi:[1,0]
	v_pk_mul_f32 v[48:49], v[176:177], v[52:53]
	v_pk_mul_f32 v[50:51], v[178:179], v[54:55]
	v_cvt_pk_bf16_f32 v48, v48, v49
	s_nop 0
	v_cvt_pk_bf16_f32 v49, v50, v51
	global_store_dwordx2 v[38:39], v[48:49], off offset:512
	v_pk_mul_f32 v[22:23], v[180:181], v[22:23]
	v_pk_mul_f32 v[24:25], v[182:183], v[24:25]
	v_cvt_pk_bf16_f32 v22, v22, v23
	s_nop 0
	v_cvt_pk_bf16_f32 v23, v24, v25
	global_store_dwordx2 v[38:39], v[22:23], off offset:1024
	v_pk_mul_f32 v[18:19], v[18:19], v[184:185]
	v_pk_mul_f32 v[20:21], v[20:21], v[186:187]
	v_cvt_pk_bf16_f32 v18, v18, v19
	s_nop 0
	v_cvt_pk_bf16_f32 v19, v20, v21
	global_store_dwordx2 v[38:39], v[18:19], off offset:1536
	v_pk_mul_f32 v[14:15], v[14:15], v[188:189]
	v_pk_mul_f32 v[16:17], v[16:17], v[190:191]
	v_cvt_pk_bf16_f32 v14, v14, v15
	s_nop 0
	v_cvt_pk_bf16_f32 v15, v16, v17
	global_store_dwordx2 v[38:39], v[14:15], off offset:2048
	v_pk_mul_f32 v[10:11], v[10:11], v[192:193]
	v_pk_mul_f32 v[12:13], v[12:13], v[194:195]
	v_cvt_pk_bf16_f32 v10, v10, v11
	s_nop 0
	v_cvt_pk_bf16_f32 v11, v12, v13
	global_store_dwordx2 v[38:39], v[10:11], off offset:2560
	v_pk_mul_f32 v[6:7], v[6:7], v[196:197]
	v_pk_mul_f32 v[8:9], v[8:9], v[198:199]
	v_cvt_pk_bf16_f32 v6, v6, v7
	s_nop 0
	v_cvt_pk_bf16_f32 v7, v8, v9
	global_store_dwordx2 v[38:39], v[6:7], off offset:3072
	v_pk_mul_f32 v[2:3], v[2:3], v[200:201]
	v_pk_mul_f32 v[4:5], v[4:5], v[202:203]
	v_cvt_pk_bf16_f32 v2, v2, v3
	s_nop 0
	v_cvt_pk_bf16_f32 v3, v4, v5
	global_store_dwordx2 v[38:39], v[2:3], off offset:3584
	v_lshl_add_u64 v[38:39], v[38:39], 0, s[82:83]
	s_cbranch_scc1 .LBB0_73

; __device__ __forceinline__ unsigned xb_ld(unsigned* p)              { return __hip_atomic_load(p, __ATOMIC_RELAXED, __HIP_MEMORY_SCOPE_AGENT); }
; __device__ __forceinline__ unsigned xb_add(unsigned* p, unsigned v) { return __hip_atomic_fetch_add(p, v, __ATOMIC_RELAXED, __HIP_MEMORY_SCOPE_AGENT); }
; #define XB_SPIN(cond, bar) do { unsigned _sp = 0; while (cond) { __builtin_amdgcn_s_sleep(1); \
;     if ((++_sp & 255u) == 0u) { if (xb_ld(&(bar)[XB_TMO])) break; if (_sp > XB_SPIN_CAP) { atomicAdd(&(bar)[XB_TMO], 1u); break; } } } } while (0)
; __device__ __forceinline__ void xcd_barrier(const XcdBarrier& b) {
;     ...
;         const unsigned old = xb_add(&bar[XB_XSUB(b.x)], 1u);
;         const unsigned gen = old / nloc;
;         if (old + 1u == (gen + 1u) * nloc) {
;             __builtin_amdgcn_fence(__ATOMIC_RELEASE, "agent");
;             asm volatile("s_waitcnt vmcnt(0)" ::: "memory");
;             const unsigned og = xb_add(&bar[XB_TOP], 1u);
;             const unsigned tg = og / nx;
;             if (og + 1u == (tg + 1u) * nx) xb_add(&bar[XB_TOPGEN], 1u);
;             else XB_SPIN(xb_ld(&bar[XB_TOPGEN]) == tg, bar);
;             __builtin_amdgcn_fence(__ATOMIC_ACQUIRE, "agent");
;             xb_add(&bar[XB_XGEN(b.x)], 1u);
;             asm volatile("s_waitcnt vmcnt(0)" ::: "memory");
;         } else {
;             XB_SPIN(xb_ld(&bar[XB_XGEN(b.x)]) == gen, bar);
.LBB0_129:
	v_readlane_b32 s4, v236, 18
	s_lshl_b32 s4, s4, 8
	s_add_u32 s4, s28, s4
	s_addc_u32 s5, s29, 0
	v_mov_b32_e32 v1, 0x1000
	v_mov_b32_e32 v3, 1
	global_atomic_add v3, v1, v3, s[4:5] offset:1024 sc0
	v_cvt_f32_u32_e32 v1, v2
	v_sub_u32_e32 v4, 0, v2
	v_rcp_iflag_f32_e32 v1, v1
	s_nop 0
	v_mul_f32_e32 v1, 0x4f7ffffe, v1
	v_cvt_u32_f32_e32 v1, v1
	v_mul_lo_u32 v4, v4, v1
	v_mul_hi_u32 v4, v1, v4
	v_add_u32_e32 v1, v1, v4
	s_waitcnt vmcnt(0)
	v_mul_hi_u32 v1, v3, v1
	v_mul_lo_u32 v4, v1, v2
	v_sub_u32_e32 v4, v3, v4
	v_add_u32_e32 v5, 1, v1
	v_cmp_ge_u32_e32 vcc, v4, v2
	v_add_u32_e32 v3, 1, v3
	s_nop 0
	v_cndmask_b32_e32 v1, v1, v5, vcc
	v_sub_u32_e32 v5, v4, v2
	v_cndmask_b32_e32 v4, v4, v5, vcc
	v_add_u32_e32 v5, 1, v1
	v_cmp_ge_u32_e32 vcc, v4, v2
	s_nop 1
	v_cndmask_b32_e32 v1, v1, v5, vcc
	v_mul_lo_u32 v4, v2, v1
	v_add_u32_e32 v2, v4, v2
	v_cmp_ne_u32_e32 vcc, v3, v2
	s_and_saveexec_b64 s[6:7], vcc
	s_xor_b64 s[6:7], exec, s[6:7]
	s_cbranch_execz .LBB0_143
	s_waitcnt lgkmcnt(0)
	v_mov_b32_e32 v0, 0x2000
	global_load_dword v0, v0, s[4:5] offset:1024 sc1
	s_add_u32 s10, s28, 0x3500
	s_addc_u32 s11, s29, 0
	s_waitcnt vmcnt(0)
	v_cmp_eq_u32_e32 vcc, v0, v1
	s_and_saveexec_b64 s[8:9], vcc
	s_cbranch_execz .LBB0_142
	s_mov_b32 s22, 1
	s_mov_b64 s[12:13], 0
	v_mov_b32_e32 v0, 0
	s_branch .LBB0_133

; __device__ __forceinline__ unsigned pk2(float lo, float hi) { unsigned r; asm("v_cvt_pk_bf16_f32 %0, %1, %2" : "=v"(r) : "v"(lo), "v"(hi)); return r; }
; __device__ __forceinline__ void p_dilated(const Args& a, LAS unsigned char* lds, const Ctx& c) {
;     ...
;     for (int i = c.gt; i < MTOK * 128; i += c.NGT) {
;         const int row = i >> 7, ch8 = i & 127, gi = ch8 >> 5, w = 2 << gi, t = row & (SEQ - 1), cnt = (t + 1 < w) ? t + 1 : w;
;         float s[8], u0[8];
; #pragma unroll
;         for (int j = 0; j < 8; ++j) { s[j] = 0.f; u0[j] = 0.f; }
;         for (int k = 0; k < cnt; ++k) { const u32x4 v = *(const u32x4*)(PROJ + (size_t)(row - k) * LDP0 + ch8 * 8);
;             const float f[8] = {bflo(v.x), bfhi(v.x), bflo(v.y), bfhi(v.y), bflo(v.z), bfhi(v.z), bflo(v.w), bfhi(v.w)};
; #pragma unroll
;             for (int j = 0; j < 8; ++j) { s[j] += f[j]; u0[j] = (k == 0) ? f[j] : u0[j]; } }
;         const float ic = 1.0f / (float)cnt; u32x4 o;
;         o.x = pk2(s[0] * ic - u0[0], s[1] * ic - u0[1]); o.y = pk2(s[2] * ic - u0[2], s[3] * ic - u0[3]); o.z = pk2(s[4] * ic - u0[4], s[5] * ic - u0[5]); o.w = pk2(s[6] * ic - u0[6], s[7] * ic - u0[7]);
;         *(u32x4*)(POOLED + (size_t)row * 1024 + ch8 * 8) = o; }
.LBB0_222:
	v_ashrrev_i32_e32 v6, 7, v27
	v_mad_i64_i32 v[8:9], s[8:9], v6, s10, v[0:1]
	global_load_dwordx4 v[12:15], v[8:9], off
	v_and_b32_e32 v7, 0xfff, v6
	v_add_u32_e32 v8, 1, v7
	v_min_u32_e32 v28, v8, v26
	v_mad_i64_i32 v[24:25], s[8:9], v6, s10, 0
	s_mov_b64 s[6:7], exec
	v_lshl_add_u64 v[24:25], v[4:5], 0, v[24:25]
	v_cmp_lt_u32_e32 vcc, 1, v28
	s_and_b64 exec, exec, vcc
	s_cbranch_execz .Lpool_issued
	global_load_dwordx4 v[40:43], v[24:25], off
	v_lshl_add_u64 v[24:25], v[24:25], 0, s[4:5]
	v_cmp_lt_u32_e32 vcc, 2, v28
	s_and_b64 exec, exec, vcc
	s_cbranch_execz .Lpool_issued
	global_load_dwordx4 v[44:47], v[24:25], off
	v_lshl_add_u64 v[24:25], v[24:25], 0, s[4:5]
	v_cmp_lt_u32_e32 vcc, 3, v28
	s_and_b64 exec, exec, vcc
	s_cbranch_execz .Lpool_issued
	global_load_dwordx4 v[48:51], v[24:25], off
	v_lshl_add_u64 v[24:25], v[24:25], 0, s[4:5]
	v_cmp_lt_u32_e32 vcc, 4, v28
	s_and_b64 exec, exec, vcc
	s_cbranch_execz .Lpool_issued
	global_load_dwordx4 v[52:55], v[24:25], off
	v_lshl_add_u64 v[24:25], v[24:25], 0, s[4:5]
	v_cmp_lt_u32_e32 vcc, 5, v28
	s_and_b64 exec, exec, vcc
	s_cbranch_execz .Lpool_issued
	global_load_dwordx4 v[56:59], v[24:25], off
	v_lshl_add_u64 v[24:25], v[24:25], 0, s[4:5]
	v_cmp_lt_u32_e32 vcc, 6, v28
	s_and_b64 exec, exec, vcc
	s_cbranch_execz .Lpool_issued
	global_load_dwordx4 v[60:63], v[24:25], off
	v_lshl_add_u64 v[24:25], v[24:25], 0, s[4:5]
	v_cmp_lt_u32_e32 vcc, 7, v28
	s_and_b64 exec, exec, vcc
	s_cbranch_execz .Lpool_issued
	global_load_dwordx4 v[64:67], v[24:25], off
	v_lshl_add_u64 v[24:25], v[24:25], 0, s[4:5]
	v_cmp_lt_u32_e32 vcc, 8, v28
	s_and_b64 exec, exec, vcc
	s_cbranch_execz .Lpool_issued
	global_load_dwordx4 v[68:71], v[24:25], off
	v_lshl_add_u64 v[24:25], v[24:25], 0, s[4:5]
	v_cmp_lt_u32_e32 vcc, 9, v28
	s_and_b64 exec, exec, vcc
	s_cbranch_execz .Lpool_issued
	global_load_dwordx4 v[72:75], v[24:25], off
	v_lshl_add_u64 v[24:25], v[24:25], 0, s[4:5]
	v_cmp_lt_u32_e32 vcc, 10, v28
	s_and_b64 exec, exec, vcc
	s_cbranch_execz .Lpool_issued
	global_load_dwordx4 v[76:79], v[24:25], off
	v_lshl_add_u64 v[24:25], v[24:25], 0, s[4:5]
	v_cmp_lt_u32_e32 vcc, 11, v28
	s_and_b64 exec, exec, vcc
	s_cbranch_execz .Lpool_issued
	global_load_dwordx4 v[80:83], v[24:25], off
	v_lshl_add_u64 v[24:25], v[24:25], 0, s[4:5]
	v_cmp_lt_u32_e32 vcc, 12, v28
	s_and_b64 exec, exec, vcc
	s_cbranch_execz .Lpool_issued
	global_load_dwordx4 v[84:87], v[24:25], off
	v_lshl_add_u64 v[24:25], v[24:25], 0, s[4:5]
	v_cmp_lt_u32_e32 vcc, 13, v28
	s_and_b64 exec, exec, vcc
	s_cbranch_execz .Lpool_issued
	global_load_dwordx4 v[88:91], v[24:25], off
	v_lshl_add_u64 v[24:25], v[24:25], 0, s[4:5]
	v_cmp_lt_u32_e32 vcc, 14, v28
	s_and_b64 exec, exec, vcc
	s_cbranch_execz .Lpool_issued
	global_load_dwordx4 v[92:95], v[24:25], off
	v_lshl_add_u64 v[24:25], v[24:25], 0, s[4:5]
	v_cmp_lt_u32_e32 vcc, 15, v28
	s_and_b64 exec, exec, vcc
	s_cbranch_execz .Lpool_issued
	global_load_dwordx4 v[96:99], v[24:25], off
.Lpool_issued:
	s_mov_b64 exec, s[6:7]
	s_waitcnt vmcnt(0)
	v_lshlrev_b32_e32 v8, 16, v12
	v_and_b32_e32 v9, 0xffff0000, v12
	v_lshlrev_b32_e32 v10, 16, v13
	v_and_b32_e32 v11, 0xffff0000, v13
	v_lshlrev_b32_e32 v12, 16, v14
	v_and_b32_e32 v13, 0xffff0000, v14
	v_lshlrev_b32_e32 v14, 16, v15
	v_and_b32_e32 v15, 0xffff0000, v15
	v_pk_add_f32 v[16:17], v[14:15], 0 op_sel_hi:[1,0]
	v_pk_add_f32 v[18:19], v[12:13], 0 op_sel_hi:[1,0]
	v_pk_add_f32 v[20:21], v[10:11], 0 op_sel_hi:[1,0]
	v_pk_add_f32 v[22:23], v[8:9], 0 op_sel_hi:[1,0]
	v_cmp_lt_u32_e32 vcc, 1, v28
	s_and_b64 exec, exec, vcc
	s_cbranch_execz .LBB0_221
	v_lshlrev_b32_e32 v34, 16, v40
	v_and_b32_e32 v35, 0xffff0000, v40
	v_lshlrev_b32_e32 v30, 16, v41
	v_and_b32_e32 v31, 0xffff0000, v41
	v_lshlrev_b32_e32 v36, 16, v42
	v_and_b32_e32 v37, 0xffff0000, v42
	v_lshlrev_b32_e32 v32, 16, v43
	v_and_b32_e32 v33, 0xffff0000, v43
	v_pk_add_f32 v[22:23], v[22:23], v[34:35]
	v_pk_add_f32 v[20:21], v[20:21], v[30:31]
	v_pk_add_f32 v[18:19], v[18:19], v[36:37]
	v_pk_add_f32 v[16:17], v[16:17], v[32:33]
	v_cmp_lt_u32_e32 vcc, 2, v28
	s_and_b64 exec, exec, vcc
	s_cbranch_execz .LBB0_221
	v_lshlrev_b32_e32 v34, 16, v44
	v_and_b32_e32 v35, 0xffff0000, v44
	v_lshlrev_b32_e32 v30, 16, v45
	v_and_b32_e32 v31, 0xffff0000, v45
	v_lshlrev_b32_e32 v36, 16, v46
	v_and_b32_e32 v37, 0xffff0000, v46
	v_lshlrev_b32_e32 v32, 16, v47
	v_and_b32_e32 v33, 0xffff0000, v47
	v_pk_add_f32 v[22:23], v[22:23], v[34:35]
	v_pk_add_f32 v[20:21], v[20:21], v[30:31]
	v_pk_add_f32 v[18:19], v[18:19], v[36:37]
	v_pk_add_f32 v[16:17], v[16:17], v[32:33]
	v_cmp_lt_u32_e32 vcc, 3, v28
	s_and_b64 exec, exec, vcc
	s_cbranch_execz .LBB0_221
	v_lshlrev_b32_e32 v34, 16, v48
	v_and_b32_e32 v35, 0xffff0000, v48
	v_lshlrev_b32_e32 v30, 16, v49
	v_and_b32_e32 v31, 0xffff0000, v49
	v_lshlrev_b32_e32 v36, 16, v50
	v_and_b32_e32 v37, 0xffff0000, v50
	v_lshlrev_b32_e32 v32, 16, v51
	v_and_b32_e32 v33, 0xffff0000, v51
	v_pk_add_f32 v[22:23], v[22:23], v[34:35]
	v_pk_add_f32 v[20:21], v[20:21], v[30:31]
	v_pk_add_f32 v[18:19], v[18:19], v[36:37]
	v_pk_add_f32 v[16:17], v[16:17], v[32:33]
	v_cmp_lt_u32_e32 vcc, 4, v28
	s_and_b64 exec, exec, vcc
	s_cbranch_execz .LBB0_221
	v_lshlrev_b32_e32 v34, 16, v52
	v_and_b32_e32 v35, 0xffff0000, v52
	v_lshlrev_b32_e32 v30, 16, v53
	v_and_b32_e32 v31, 0xffff0000, v53
	v_lshlrev_b32_e32 v36, 16, v54
	v_and_b32_e32 v37, 0xffff0000, v54
	v_lshlrev_b32_e32 v32, 16, v55
	v_and_b32_e32 v33, 0xffff0000, v55
	v_pk_add_f32 v[22:23], v[22:23], v[34:35]
	v_pk_add_f32 v[20:21], v[20:21], v[30:31]
	v_pk_add_f32 v[18:19], v[18:19], v[36:37]
	v_pk_add_f32 v[16:17], v[16:17], v[32:33]
	v_cmp_lt_u32_e32 vcc, 5, v28
	s_and_b64 exec, exec, vcc
	s_cbranch_execz .LBB0_221
; __device__ __forceinline__ void p_dilated(const Args& a, LAS unsigned char* lds, const Ctx& c) {
;     ...
;         for (int k = 0; k < cnt; ++k) { const u32x4 v = *(const u32x4*)(PROJ + (size_t)(row - k) * LDP0 + ch8 * 8);
;             const float f[8] = {bflo(v.x), bfhi(v.x), bflo(v.y), bfhi(v.y), bflo(v.z), bfhi(v.z), bflo(v.w), bfhi(v.w)};
; #pragma unroll
;             for (int j = 0; j < 8; ++j) { s[j] += f[j]; u0[j] = (k == 0) ? f[j] : u0[j]; } }
	v_lshlrev_b32_e32 v34, 16, v56
	v_and_b32_e32 v35, 0xffff0000, v56
	v_lshlrev_b32_e32 v30, 16, v57
	v_and_b32_e32 v31, 0xffff0000, v57
	v_lshlrev_b32_e32 v36, 16, v58
	v_and_b32_e32 v37, 0xffff0000, v58
	v_lshlrev_b32_e32 v32, 16, v59
	v_and_b32_e32 v33, 0xffff0000, v59
	v_pk_add_f32 v[22:23], v[22:23], v[34:35]
	v_pk_add_f32 v[20:21], v[20:21], v[30:31]
	v_pk_add_f32 v[18:19], v[18:19], v[36:37]
	v_pk_add_f32 v[16:17], v[16:17], v[32:33]
	v_cmp_lt_u32_e32 vcc, 6, v28
	s_and_b64 exec, exec, vcc
	s_cbranch_execz .LBB0_221
	v_lshlrev_b32_e32 v34, 16, v60
	v_and_b32_e32 v35, 0xffff0000, v60
	v_lshlrev_b32_e32 v30, 16, v61
	v_and_b32_e32 v31, 0xffff0000, v61
	v_lshlrev_b32_e32 v36, 16, v62
	v_and_b32_e32 v37, 0xffff0000, v62
	v_lshlrev_b32_e32 v32, 16, v63
	v_and_b32_e32 v33, 0xffff0000, v63
	v_pk_add_f32 v[22:23], v[22:23], v[34:35]
	v_pk_add_f32 v[20:21], v[20:21], v[30:31]
	v_pk_add_f32 v[18:19], v[18:19], v[36:37]
	v_pk_add_f32 v[16:17], v[16:17], v[32:33]
	v_cmp_lt_u32_e32 vcc, 7, v28
	s_and_b64 exec, exec, vcc
	s_cbranch_execz .LBB0_221
	v_lshlrev_b32_e32 v34, 16, v64
	v_and_b32_e32 v35, 0xffff0000, v64
	v_lshlrev_b32_e32 v30, 16, v65
	v_and_b32_e32 v31, 0xffff0000, v65
	v_lshlrev_b32_e32 v36, 16, v66
	v_and_b32_e32 v37, 0xffff0000, v66
	v_lshlrev_b32_e32 v32, 16, v67
	v_and_b32_e32 v33, 0xffff0000, v67
	v_pk_add_f32 v[22:23], v[22:23], v[34:35]
	v_pk_add_f32 v[20:21], v[20:21], v[30:31]
	v_pk_add_f32 v[18:19], v[18:19], v[36:37]
	v_pk_add_f32 v[16:17], v[16:17], v[32:33]
	v_cmp_lt_u32_e32 vcc, 8, v28
	s_and_b64 exec, exec, vcc
	s_cbranch_execz .LBB0_221
	v_lshlrev_b32_e32 v34, 16, v68
	v_and_b32_e32 v35, 0xffff0000, v68
	v_lshlrev_b32_e32 v30, 16, v69
	v_and_b32_e32 v31, 0xffff0000, v69
	v_lshlrev_b32_e32 v36, 16, v70
	v_and_b32_e32 v37, 0xffff0000, v70
	v_lshlrev_b32_e32 v32, 16, v71
	v_and_b32_e32 v33, 0xffff0000, v71
	v_pk_add_f32 v[22:23], v[22:23], v[34:35]
	v_pk_add_f32 v[20:21], v[20:21], v[30:31]
	v_pk_add_f32 v[18:19], v[18:19], v[36:37]
	v_pk_add_f32 v[16:17], v[16:17], v[32:33]
	v_cmp_lt_u32_e32 vcc, 9, v28
	s_and_b64 exec, exec, vcc
	s_cbranch_execz .LBB0_221
	v_lshlrev_b32_e32 v34, 16, v72
	v_and_b32_e32 v35, 0xffff0000, v72
	v_lshlrev_b32_e32 v30, 16, v73
	v_and_b32_e32 v31, 0xffff0000, v73
	v_lshlrev_b32_e32 v36, 16, v74
	v_and_b32_e32 v37, 0xffff0000, v74
	v_lshlrev_b32_e32 v32, 16, v75
	v_and_b32_e32 v33, 0xffff0000, v75
	v_pk_add_f32 v[22:23], v[22:23], v[34:35]
	v_pk_add_f32 v[20:21], v[20:21], v[30:31]
	v_pk_add_f32 v[18:19], v[18:19], v[36:37]
	v_pk_add_f32 v[16:17], v[16:17], v[32:33]
	v_cmp_lt_u32_e32 vcc, 10, v28
	s_and_b64 exec, exec, vcc
	s_cbranch_execz .LBB0_221
	v_lshlrev_b32_e32 v34, 16, v76
	v_and_b32_e32 v35, 0xffff0000, v76
	v_lshlrev_b32_e32 v30, 16, v77
	v_and_b32_e32 v31, 0xffff0000, v77
	v_lshlrev_b32_e32 v36, 16, v78
	v_and_b32_e32 v37, 0xffff0000, v78
	v_lshlrev_b32_e32 v32, 16, v79
	v_and_b32_e32 v33, 0xffff0000, v79
	v_pk_add_f32 v[22:23], v[22:23], v[34:35]
	v_pk_add_f32 v[20:21], v[20:21], v[30:31]
	v_pk_add_f32 v[18:19], v[18:19], v[36:37]
	v_pk_add_f32 v[16:17], v[16:17], v[32:33]
	v_cmp_lt_u32_e32 vcc, 11, v28
	s_and_b64 exec, exec, vcc
	s_cbranch_execz .LBB0_221
	v_lshlrev_b32_e32 v34, 16, v80
	v_and_b32_e32 v35, 0xffff0000, v80
	v_lshlrev_b32_e32 v30, 16, v81
	v_and_b32_e32 v31, 0xffff0000, v81
	v_lshlrev_b32_e32 v36, 16, v82
	v_and_b32_e32 v37, 0xffff0000, v82
	v_lshlrev_b32_e32 v32, 16, v83
	v_and_b32_e32 v33, 0xffff0000, v83
	v_pk_add_f32 v[22:23], v[22:23], v[34:35]
	v_pk_add_f32 v[20:21], v[20:21], v[30:31]
	v_pk_add_f32 v[18:19], v[18:19], v[36:37]
	v_pk_add_f32 v[16:17], v[16:17], v[32:33]
	v_cmp_lt_u32_e32 vcc, 12, v28
	s_and_b64 exec, exec, vcc
	s_cbranch_execz .LBB0_221
	v_lshlrev_b32_e32 v34, 16, v84
	v_and_b32_e32 v35, 0xffff0000, v84
	v_lshlrev_b32_e32 v30, 16, v85
	v_and_b32_e32 v31, 0xffff0000, v85
	v_lshlrev_b32_e32 v36, 16, v86
	v_and_b32_e32 v37, 0xffff0000, v86
	v_lshlrev_b32_e32 v32, 16, v87
	v_and_b32_e32 v33, 0xffff0000, v87
	v_pk_add_f32 v[22:23], v[22:23], v[34:35]
	v_pk_add_f32 v[20:21], v[20:21], v[30:31]
	v_pk_add_f32 v[18:19], v[18:19], v[36:37]
	v_pk_add_f32 v[16:17], v[16:17], v[32:33]
	v_cmp_lt_u32_e32 vcc, 13, v28
	s_and_b64 exec, exec, vcc
	s_cbranch_execz .LBB0_221
	v_lshlrev_b32_e32 v34, 16, v88
	v_and_b32_e32 v35, 0xffff0000, v88
	v_lshlrev_b32_e32 v30, 16, v89
	v_and_b32_e32 v31, 0xffff0000, v89
	v_lshlrev_b32_e32 v36, 16, v90
	v_and_b32_e32 v37, 0xffff0000, v90
	v_lshlrev_b32_e32 v32, 16, v91
	v_and_b32_e32 v33, 0xffff0000, v91
	v_pk_add_f32 v[22:23], v[22:23], v[34:35]
	v_pk_add_f32 v[20:21], v[20:21], v[30:31]
	v_pk_add_f32 v[18:19], v[18:19], v[36:37]
	v_pk_add_f32 v[16:17], v[16:17], v[32:33]
	v_cmp_lt_u32_e32 vcc, 14, v28
	s_and_b64 exec, exec, vcc
	s_cbranch_execz .LBB0_221
	v_lshlrev_b32_e32 v34, 16, v92
	v_and_b32_e32 v35, 0xffff0000, v92
	v_lshlrev_b32_e32 v30, 16, v93
	v_and_b32_e32 v31, 0xffff0000, v93
	v_lshlrev_b32_e32 v36, 16, v94
	v_and_b32_e32 v37, 0xffff0000, v94
	v_lshlrev_b32_e32 v32, 16, v95
	v_and_b32_e32 v33, 0xffff0000, v95
	v_pk_add_f32 v[22:23], v[22:23], v[34:35]
	v_pk_add_f32 v[20:21], v[20:21], v[30:31]
	v_pk_add_f32 v[18:19], v[18:19], v[36:37]
	v_pk_add_f32 v[16:17], v[16:17], v[32:33]
	v_cmp_lt_u32_e32 vcc, 15, v28
	s_and_b64 exec, exec, vcc
	s_cbranch_execz .LBB0_221
	v_lshlrev_b32_e32 v34, 16, v96
	v_and_b32_e32 v35, 0xffff0000, v96
	v_lshlrev_b32_e32 v30, 16, v97
	v_and_b32_e32 v31, 0xffff0000, v97
	v_lshlrev_b32_e32 v36, 16, v98
	v_and_b32_e32 v37, 0xffff0000, v98
	v_lshlrev_b32_e32 v32, 16, v99
	v_and_b32_e32 v33, 0xffff0000, v99
	v_pk_add_f32 v[22:23], v[22:23], v[34:35]
	v_pk_add_f32 v[20:21], v[20:21], v[30:31]
	v_pk_add_f32 v[18:19], v[18:19], v[36:37]
	v_pk_add_f32 v[16:17], v[16:17], v[32:33]
	s_branch .LBB0_221

; __device__ __forceinline__ void resid_rows(const float* prev, const bf16_t* Y, const float* ga, const bf16_t* F, const float* gc, float* xout, const float* gb, bf16_t* hn, int gw, int NGW, int lane) {
;     for (int m = gw; m < MTOK; m += NGW) {
;         f32x4 y[8]; float s = 0.f;
; #pragma unroll
;         for (int j = 0; j < 8; ++j) { const u32x2 w = *(const u32x2*)(Y + (size_t)m * LDH + 4 * lane + 256 * j); y[j] = (f32x4){bflo(w.x), bfhi(w.x), bflo(w.y), bfhi(w.y)};
;             s += (y[j][0] * y[j][0] + y[j][1] * y[j][1]) + (y[j][2] * y[j][2] + y[j][3] * y[j][3]); }
;         const float rs = 1.0f / sqrtf(wave_sum(s) * (1.0f / D_MODEL) + EPS);
;         f32x4 x1[8];
; #pragma unroll
;         for (int j = 0; j < 8; ++j) { const f32x4 pv = *(const f32x4*)(prev + (size_t)m * D_MODEL + 4 * lane + 256 * j); const f32x4 gv = *(const f32x4*)(ga + 4 * lane + 256 * j);
;             x1[j] = pv + y[j] * rs * gv; }
.LBB0_449:
	s_cmp_lt_i32 s30, 6
	s_cselect_b64 s[2:3], -1, 0
	s_and_b64 s[2:3], s[2:3], s[0:1]
	s_cmpk_lt_i32 s34, 0x4000
	s_cselect_b64 s[64:65], -1, 0
	s_and_b64 s[0:1], s[2:3], s[64:65]
	s_andn2_b64 vcc, exec, s[0:1]
	v_mbcnt_lo_u32_b32 v169, -1, 0
	v_lshlrev_b32_e32 v148, 4, v164
	s_cbranch_vccnz .LBB0_452
	s_waitcnt vmcnt(0)
	v_mbcnt_hi_u32_b32 v0, -1, v169
	v_and_b32_e32 v1, 64, v0
	v_add_u32_e32 v1, 64, v1
	v_xor_b32_e32 v2, 1, v0
	v_cmp_lt_i32_e32 vcc, v2, v1
	v_readlane_b32 s4, v236, 2
	v_mov_b32_e32 v149, 0
	v_cndmask_b32_e32 v2, v0, v2, vcc
	v_lshlrev_b32_e32 v110, 2, v2
	v_xor_b32_e32 v2, 2, v0
	v_cmp_lt_i32_e32 vcc, v2, v1
	v_readlane_b32 s6, v236, 4
	v_readlane_b32 s7, v236, 5
	v_cndmask_b32_e32 v2, v0, v2, vcc
	v_lshlrev_b32_e32 v111, 2, v2
	v_xor_b32_e32 v2, 4, v0
	v_cmp_lt_i32_e32 vcc, v2, v1
	s_mov_b64 s[0:1], 0x2000
	s_ashr_i32 s35, s34, 31
	v_cndmask_b32_e32 v2, v0, v2, vcc
	v_lshlrev_b32_e32 v112, 2, v2
	v_xor_b32_e32 v2, 8, v0
	v_cmp_lt_i32_e32 vcc, v2, v1
	v_readlane_b32 s5, v236, 3
	v_readlane_b32 s8, v236, 6
	v_cndmask_b32_e32 v2, v0, v2, vcc
	v_lshlrev_b32_e32 v113, 2, v2
	v_xor_b32_e32 v2, 16, v0
	v_cmp_lt_i32_e32 vcc, v2, v1
	v_mov_b32_e32 v116, 0x358637bd
	v_mov_b32_e32 v117, 0x260
	v_cndmask_b32_e32 v2, v0, v2, vcc
	v_lshlrev_b32_e32 v114, 2, v2
	v_xor_b32_e32 v2, 32, v0
	v_cmp_lt_i32_e32 vcc, v2, v1
	s_mov_b32 s8, s34
	v_readlane_b32 s9, v236, 7
	v_cndmask_b32_e32 v0, v0, v2, vcc
	v_lshlrev_b32_e32 v115, 2, v0
	v_lshl_add_u64 v[0:1], s[6:7], 0, v[148:149]
	v_lshl_add_u64 v[68:69], v[0:1], 0, s[0:1]
	s_mov_b64 s[0:1], 0x4000
	v_lshl_add_u64 v[70:71], v[0:1], 0, s[0:1]
	s_mov_b64 s[0:1], 0x5000
	v_lshl_add_u64 v[72:73], v[0:1], 0, s[0:1]
	s_mov_b64 s[0:1], 0x5400
	v_lshl_add_u64 v[74:75], v[0:1], 0, s[0:1]
	s_mov_b64 s[0:1], 0x5800
	v_lshl_add_u64 v[76:77], v[0:1], 0, s[0:1]
	s_mov_b64 s[0:1], 0x5c00
	v_lshl_add_u64 v[78:79], v[0:1], 0, s[0:1]
	s_mov_b64 s[0:1], 0x3000
	v_lshl_add_u64 v[80:81], v[0:1], 0, s[0:1]
	s_mov_b64 s[0:1], 0x3400
	v_lshl_add_u64 v[82:83], v[0:1], 0, s[0:1]
	s_mov_b64 s[0:1], 0x3800
	v_lshl_add_u64 v[84:85], v[0:1], 0, s[0:1]
	s_mov_b64 s[0:1], 0x3c00
	v_lshl_add_u64 v[86:87], v[0:1], 0, s[0:1]
	s_lshl_b64 s[0:1], s[34:35], 13
	v_and_b32_e32 v2, 63, v168
	s_add_u32 s0, s4, s0
	v_lshlrev_b32_e32 v0, 4, v2
	v_mov_b32_e32 v1, v149
	s_addc_u32 s1, s5, s1
	v_lshl_add_u64 v[0:1], s[0:1], 0, v[0:1]
	s_mov_b64 s[0:1], 0x1000
	s_ashr_i32 s61, s60, 31
	v_lshl_add_u64 v[88:89], v[0:1], 0, s[0:1]
	s_lshl_b64 s[4:5], s[60:61], 13
	v_readlane_b32 s0, v236, 19
	s_add_u32 s0, s28, s0
	v_lshlrev_b32_e32 v0, 3, v2
	v_mov_b32_e32 v1, v149
	s_addc_u32 s1, s29, s81
	v_lshl_add_u64 v[0:1], s[0:1], 0, v[0:1]
	s_mov_b64 s[0:1], 0x8000000
	v_lshl_add_u64 v[90:91], v[0:1], 0, s[0:1]
	s_mov_b32 s6, 0xf800000
	s_mov_b32 s7, 0x4400000
	v_readlane_b32 s10, v236, 8
	v_readlane_b32 s11, v236, 9
	v_readlane_b32 s12, v236, 10
	v_readlane_b32 s13, v236, 11
	v_readlane_b32 s14, v236, 12
	v_readlane_b32 s15, v236, 13
	v_readlane_b32 s16, v236, 14
	v_readlane_b32 s17, v236, 15
	v_readlane_b32 s18, v236, 16
	v_readlane_b32 s19, v236, 17
	global_load_dwordx4 v[176:179], v[70:71], off offset:1024
	global_load_dwordx4 v[180:183], v[70:71], off offset:2048
	global_load_dwordx4 v[184:187], v[70:71], off offset:3072
	global_load_dwordx4 v[188:191], v[72:73], off
	global_load_dwordx4 v[192:195], v[74:75], off
	global_load_dwordx4 v[196:199], v[76:77], off
	global_load_dwordx4 v[200:203], v[78:79], off
.LBB0_451:
	global_load_dwordx2 v[92:93], v[90:91], off
	global_load_dwordx2 v[94:95], v[90:91], off offset:512
	global_load_dwordx2 v[96:97], v[90:91], off offset:1024
	global_load_dwordx2 v[98:99], v[90:91], off offset:1536
	global_load_dwordx2 v[102:103], v[90:91], off offset:2048
	global_load_dwordx2 v[104:105], v[90:91], off offset:2560
	global_load_dwordx2 v[106:107], v[90:91], off offset:3072
	global_load_dwordx2 v[108:109], v[90:91], off offset:3584
	global_load_dwordx4 v[0:3], v[88:89], off offset:-4096
	global_load_dwordx4 v[4:7], v[88:89], off offset:-3072
	global_load_dwordx4 v[12:15], v[68:69], off
	global_load_dwordx4 v[8:11], v[68:69], off offset:1024
	global_load_dwordx4 v[16:19], v[88:89], off offset:-2048
	global_load_dwordx4 v[20:23], v[88:89], off offset:-1024
	global_load_dwordx4 v[28:31], v[68:69], off offset:2048
	global_load_dwordx4 v[24:27], v[68:69], off offset:3072
	global_load_dwordx4 v[32:35], v[88:89], off
	global_load_dwordx4 v[36:39], v[88:89], off offset:1024
	global_load_dwordx4 v[40:43], v[82:83], off
	global_load_dwordx4 v[44:47], v[84:85], off
	global_load_dwordx4 v[48:51], v[88:89], off offset:2048
	global_load_dwordx4 v[52:55], v[88:89], off offset:3072
	global_load_dwordx4 v[56:59], v[86:87], off
	global_load_dwordx4 v[60:63], v[80:81], off
	global_load_dwordx4 v[64:67], v[70:71], off
	v_add_co_u32_e32 v100, vcc, s7, v90
	s_add_i32 s8, s8, s60
	s_nop 0
	v_addc_co_u32_e32 v101, vcc, 0, v91, vcc
	v_lshl_add_u64 v[88:89], v[88:89], 0, s[4:5]
	v_lshl_add_u64 v[90:91], v[90:91], 0, s[82:83]
	s_cmpk_lt_i32 s8, 0x4000
	s_waitcnt vmcnt(24)
	v_lshlrev_b32_e32 v118, 16, v92
	v_and_b32_e32 v119, 0xffff0000, v92
	v_lshlrev_b32_e32 v92, 16, v93
	v_and_b32_e32 v93, 0xffff0000, v93
	s_waitcnt vmcnt(23)
	v_lshlrev_b32_e32 v121, 16, v95
	v_lshlrev_b32_e32 v120, 16, v94
	v_and_b32_e32 v95, 0xffff0000, v95
	v_and_b32_e32 v94, 0xffff0000, v94
	s_waitcnt vmcnt(22)
	v_and_b32_e32 v123, 0xffff0000, v96
	s_waitcnt vmcnt(21)
	v_lshlrev_b32_e32 v125, 16, v98
	s_waitcnt vmcnt(17)
; __device__ __forceinline__ void resid_rows(const float* prev, const bf16_t* Y, const float* ga, const bf16_t* F, const float* gc, float* xout, const float* gb, bf16_t* hn, int gw, int NGW, int lane) {
;     ...
;         for (int j = 0; j < 8; ++j) { const u32x2 w = *(const u32x2*)(Y + (size_t)m * LDH + 4 * lane + 256 * j); y[j] = (f32x4){bflo(w.x), bfhi(w.x), bflo(w.y), bfhi(w.y)};
;             s += (y[j][0] * y[j][0] + y[j][1] * y[j][1]) + (y[j][2] * y[j][2] + y[j][3] * y[j][3]); }
;         const float rs = 1.0f / sqrtf(wave_sum(s) * (1.0f / D_MODEL) + EPS);
	v_lshlrev_b32_e32 v135, 16, v108
	v_mul_f32_e32 v124, v93, v93
	v_pk_mul_f32 v[138:139], v[94:95], v[94:95]
	v_mul_f32_e32 v134, v119, v119
	v_lshlrev_b32_e32 v122, 16, v96
	v_lshlrev_b32_e32 v96, 16, v97
	v_and_b32_e32 v97, 0xffff0000, v97
	v_lshlrev_b32_e32 v129, 16, v103
	v_lshlrev_b32_e32 v128, 16, v102
	v_and_b32_e32 v103, 0xffff0000, v103
	v_and_b32_e32 v102, 0xffff0000, v102
	v_lshlrev_b32_e32 v131, 16, v105
	v_lshlrev_b32_e32 v130, 16, v104
	v_and_b32_e32 v105, 0xffff0000, v105
	v_and_b32_e32 v104, 0xffff0000, v104
	v_mov_b32_e32 v141, v125
	v_mul_f32_e32 v140, v123, v123
	v_mov_b32_e32 v154, v120
	v_mov_b32_e32 v155, v94
	v_mov_b32_e32 v94, v121
	v_pk_fma_f32 v[160:161], v[92:93], v[92:93], v[124:125] op_sel_hi:[1,1,0]
	v_pk_fma_f32 v[120:121], v[120:121], v[120:121], v[138:139]
	v_pk_fma_f32 v[138:139], v[118:119], v[118:119], v[134:135] op_sel_hi:[1,1,0]
	v_and_b32_e32 v127, 0xffff0000, v98
	v_lshlrev_b32_e32 v98, 16, v99
	v_and_b32_e32 v99, 0xffff0000, v99
	v_mul_f32_e32 v142, v97, v97
	v_pk_mul_f32 v[144:145], v[102:103], v[102:103]
	v_pk_mul_f32 v[146:147], v[104:105], v[104:105]
	v_mov_b32_e32 v143, v135
	v_pk_fma_f32 v[162:163], v[122:123], v[122:123], v[140:141] op_sel_hi:[1,1,0]
	v_mov_b32_e32 v124, v138
	v_mov_b32_e32 v140, v160
	v_mul_f32_e32 v149, v127, v127
	v_mul_f32_e32 v153, v98, v98
	v_mul_f32_e32 v165, v99, v99
	v_mov_b32_e32 v126, v125
	v_mov_b32_e32 v156, v128
	v_mov_b32_e32 v157, v102
	v_mov_b32_e32 v102, v129
	v_mov_b32_e32 v158, v131
	v_mov_b32_e32 v159, v105
	v_pk_fma_f32 v[166:167], v[96:97], v[96:97], v[142:143] op_sel_hi:[1,1,0]
	v_pk_fma_f32 v[128:129], v[128:129], v[128:129], v[144:145]
	v_pk_fma_f32 v[144:145], v[130:131], v[130:131], v[146:147]
	v_mov_b32_e32 v131, v104
	v_pk_add_f32 v[104:105], v[138:139], v[160:161]
	v_pk_add_f32 v[120:121], v[120:121], v[120:121] op_sel:[0,1] op_sel_hi:[1,0]
	v_pk_mul_f32 v[124:125], v[124:125], v[140:141]
	v_mov_b32_e32 v163, v153
	v_mov_b32_e32 v167, v165
	v_mov_b32_e32 v121, v149
	v_mov_b32_e32 v105, v125
	v_pk_add_f32 v[140:141], v[162:163], v[166:167]
	v_pk_add_f32 v[104:105], v[104:105], v[120:121]
	v_lshlrev_b32_e32 v132, 16, v106
	v_pk_add_f32 v[104:105], v[104:105], v[140:141]
	v_and_b32_e32 v133, 0xffff0000, v106
	v_lshlrev_b32_e32 v106, 16, v107
	v_and_b32_e32 v107, 0xffff0000, v107
	v_pk_add_f32 v[128:129], v[128:129], v[128:129] op_sel:[0,1] op_sel_hi:[1,0]
	v_pk_add_f32 v[104:105], v[104:105], v[104:105] op_sel:[0,1] op_sel_hi:[1,0]
	v_and_b32_e32 v137, 0xffff0000, v108
	v_lshlrev_b32_e32 v108, 16, v109
	v_and_b32_e32 v109, 0xffff0000, v109
	v_mul_f32_e32 v150, v133, v133
	v_mul_f32_e32 v152, v107, v107
	v_mov_b32_e32 v142, v128
	v_mov_b32_e32 v134, v104
	v_mul_f32_e32 v170, v137, v137
	v_mul_f32_e32 v171, v108, v108
	v_mul_f32_e32 v172, v109, v109
	v_pk_fma_f32 v[146:147], v[132:133], v[132:133], v[150:151] op_sel_hi:[1,1,0]
	v_pk_fma_f32 v[150:151], v[106:107], v[106:107], v[152:153] op_sel_hi:[1,1,0]
	v_pk_add_f32 v[138:139], v[144:145], v[144:145] op_sel:[0,1] op_sel_hi:[1,0]
	v_pk_add_f32 v[104:105], v[104:105], v[128:129]
	v_pk_mul_f32 v[120:121], v[134:135], v[142:143]
	v_mov_b32_e32 v147, v171
	v_mov_b32_e32 v151, v172
	v_mov_b32_e32 v139, v170
	v_mov_b32_e32 v105, v121
	v_pk_add_f32 v[144:145], v[146:147], v[150:151]
	v_pk_add_f32 v[104:105], v[104:105], v[138:139]
	v_mov_b32_e32 v136, v135
	v_pk_add_f32 v[104:105], v[104:105], v[144:145]
	s_nop 0
	v_add_f32_e32 v104, v104, v105
	ds_bpermute_b32 v105, v110, v104
	s_waitcnt lgkmcnt(0)
	v_add_f32_e32 v104, v104, v105
	ds_bpermute_b32 v105, v111, v104
	s_waitcnt lgkmcnt(0)
	v_add_f32_e32 v104, v104, v105
	ds_bpermute_b32 v105, v112, v104
	s_waitcnt lgkmcnt(0)
	v_add_f32_e32 v104, v104, v105
	ds_bpermute_b32 v105, v113, v104
	s_waitcnt lgkmcnt(0)
	v_add_f32_e32 v104, v104, v105
	ds_bpermute_b32 v105, v114, v104
	s_waitcnt lgkmcnt(0)
	v_add_f32_e32 v104, v104, v105
	ds_bpermute_b32 v105, v115, v104
	s_waitcnt lgkmcnt(0)
	v_add_f32_e32 v104, v104, v105
	v_fmamk_f32 v104, v104, 0x3a000000, v116
	v_mul_f32_e32 v105, 0x4f800000, v104
	v_cmp_gt_f32_e32 vcc, s6, v104
	s_nop 1
	v_cndmask_b32_e32 v104, v104, v105, vcc
	v_sqrt_f32_e32 v105, v104
	s_nop 0
	v_add_u32_e32 v120, -1, v105
	v_add_u32_e32 v121, 1, v105
	v_fma_f32 v124, -v120, v105, v104
	v_fma_f32 v125, -v121, v105, v104
	v_cmp_ge_f32_e64 s[0:1], 0, v124
	s_nop 1
	v_cndmask_b32_e64 v105, v105, v120, s[0:1]
	v_cmp_lt_f32_e64 s[0:1], 0, v125
	s_nop 1
	v_cndmask_b32_e64 v105, v105, v121, s[0:1]
	v_mul_f32_e32 v120, 0x37800000, v105
	v_cndmask_b32_e32 v105, v105, v120, vcc
	v_cmp_class_f32_e32 vcc, v104, v117
	s_nop 1
	v_cndmask_b32_e32 v104, v105, v104, vcc
	v_div_scale_f32 v105, s[0:1], v104, v104, 1.0
	v_rcp_f32_e32 v121, v105
	v_div_scale_f32 v120, vcc, 1.0, v104, 1.0
	v_fma_f32 v124, -v105, v121, 1.0
	v_fmac_f32_e32 v121, v124, v121
	v_mul_f32_e32 v124, v120, v121
	v_fma_f32 v125, -v105, v124, v120
	v_fmac_f32_e32 v124, v125, v121
	v_fma_f32 v105, -v105, v124, v120
	v_div_fmas_f32 v105, v105, v121, v124
	v_div_fixup_f32 v104, v105, v104, 1.0
	v_pk_mul_f32 v[118:119], v[104:105], v[118:119] op_sel_hi:[0,1]
	v_pk_mul_f32 v[92:93], v[104:105], v[92:93] op_sel_hi:[0,1]
	v_pk_mul_f32 v[120:121], v[104:105], v[154:155] op_sel_hi:[0,1]
	v_pk_mul_f32 v[94:95], v[104:105], v[94:95] op_sel_hi:[0,1]
	v_pk_mul_f32 v[96:97], v[104:105], v[96:97] op_sel_hi:[0,1]
	v_pk_mul_f32 v[122:123], v[104:105], v[122:123] op_sel_hi:[0,1]
	v_pk_mul_f32 v[98:99], v[98:99], v[104:105] op_sel_hi:[1,0]
	v_pk_mul_f32 v[102:103], v[104:105], v[102:103] op_sel_hi:[0,1]
	v_pk_mul_f32 v[128:129], v[104:105], v[158:159] op_sel_hi:[0,1]
	s_waitcnt vmcnt(14)
; __device__ __forceinline__ void row_norm_store(const f32x4 (&v)[8], const float* gain, bf16_t* orow, int lane) {
;     float s = 0.f;
; #pragma unroll
;     for (int j = 0; j < 8; ++j) s += (v[j][0] * v[j][0] + v[j][1] * v[j][1]) + (v[j][2] * v[j][2] + v[j][3] * v[j][3]);
; __device__ __forceinline__ void resid_rows(const float* prev, const bf16_t* Y, const float* ga, const bf16_t* F, const float* gc, float* xout, const float* gb, bf16_t* hn, int gw, int NGW, int lane) {
;     ...
;         f32x4 x1[8];
; #pragma unroll
;         for (int j = 0; j < 8; ++j) { const f32x4 pv = *(const f32x4*)(prev + (size_t)m * D_MODEL + 4 * lane + 256 * j); const f32x4 gv = *(const f32x4*)(ga + 4 * lane + 256 * j);
;             x1[j] = pv + y[j] * rs * gv; }
	v_pk_fma_f32 v[2:3], v[14:15], v[92:93], v[2:3]
	v_pk_fma_f32 v[0:1], v[12:13], v[118:119], v[0:1]
	s_waitcnt vmcnt(13)
	v_pk_fma_f32 v[6:7], v[10:11], v[94:95], v[6:7]
	v_pk_fma_f32 v[4:5], v[8:9], v[120:121], v[4:5]
	v_pk_mul_f32 v[124:125], v[126:127], v[104:105] op_sel_hi:[1,0]
	v_pk_mul_f32 v[126:127], v[104:105], v[156:157] op_sel_hi:[0,1]
	v_pk_mul_f32 v[130:131], v[104:105], v[130:131] op_sel_hi:[0,1]
	s_waitcnt vmcnt(10)
	v_pk_fma_f32 v[8:9], v[28:29], v[122:123], v[16:17]
	v_pk_fma_f32 v[10:11], v[30:31], v[96:97], v[18:19]
	s_waitcnt vmcnt(9)
	v_pk_fma_f32 v[12:13], v[26:27], v[98:99], v[22:23]
	s_waitcnt vmcnt(1)
	v_pk_fma_f32 v[16:17], v[62:63], v[102:103], v[34:35]
	v_pk_fma_f32 v[22:23], v[42:43], v[128:129], v[38:39]
	v_mov_b32_e32 v34, v1
	v_mov_b32_e32 v35, v5
	v_mov_b32_e32 v38, v3
	v_mov_b32_e32 v39, v7
	v_pk_mul_f32 v[134:135], v[136:137], v[104:105] op_sel_hi:[1,0]
	v_pk_fma_f32 v[14:15], v[24:25], v[124:125], v[20:21]
	v_pk_fma_f32 v[18:19], v[60:61], v[126:127], v[32:33]
	v_pk_fma_f32 v[20:21], v[40:41], v[130:131], v[36:37]
	v_mov_b32_e32 v32, v0
	v_mov_b32_e32 v33, v4
	v_mov_b32_e32 v36, v2
	v_mov_b32_e32 v37, v6
	v_pk_mul_f32 v[40:41], v[10:11], v[10:11]
	v_pk_mul_f32 v[42:43], v[8:9], v[8:9]
	v_pk_mul_f32 v[34:35], v[34:35], v[34:35]
	v_pk_mul_f32 v[38:39], v[38:39], v[38:39]
	v_pk_mul_f32 v[132:133], v[104:105], v[132:133] op_sel_hi:[0,1]
	v_pk_mul_f32 v[106:107], v[104:105], v[106:107] op_sel_hi:[0,1]
	v_pk_fma_f32 v[30:31], v[134:135], v[56:57], v[52:53]
	v_pk_mov_b32 v[56:57], v[42:43], v[40:41] op_sel:[1,0]
	v_mov_b32_e32 v43, v41
	v_pk_fma_f32 v[32:33], v[32:33], v[32:33], v[34:35]
	v_pk_fma_f32 v[34:35], v[36:37], v[36:37], v[38:39]
	v_pk_fma_f32 v[24:25], v[46:47], v[106:107], v[50:51]
	v_pk_fma_f32 v[26:27], v[44:45], v[132:133], v[48:49]
	v_mul_f32_e32 v44, v14, v14
	v_mul_f32_e32 v46, v12, v12
	v_pk_add_f32 v[36:37], v[56:57], v[42:43]
	v_pk_add_f32 v[32:33], v[32:33], v[34:35]
	v_pk_fma_f32 v[40:41], v[14:15], v[14:15], v[44:45] op_sel_hi:[1,1,0]
	v_pk_fma_f32 v[44:45], v[12:13], v[12:13], v[46:47] op_sel_hi:[1,1,0]
	v_pk_add_f32 v[34:35], v[36:37], v[36:37] op_sel_hi:[0,1]
	v_pk_add_f32 v[32:33], v[32:33], v[32:33] op_sel_hi:[0,1]
	v_pk_mul_f32 v[48:49], v[22:23], v[22:23]
	v_pk_mul_f32 v[50:51], v[20:21], v[20:21]
	v_mul_f32_e32 v40, v18, v18
	v_mul_f32_e32 v44, v19, v19
	v_mul_f32_e32 v34, v16, v16
	v_mul_f32_e32 v32, v17, v17
	v_pk_mul_f32 v[104:105], v[108:109], v[104:105] op_sel_hi:[1,0]
	v_pk_mov_b32 v[46:47], v[50:51], v[48:49] op_sel:[1,0]
	v_mov_b32_e32 v51, v49
	v_pk_add_f32 v[36:37], v[40:41], v[44:45]
	v_pk_add_f32 v[32:33], v[34:35], v[32:33]
	v_pk_fma_f32 v[28:29], v[104:105], v[58:59], v[54:55]
	v_mul_f32_e32 v52, v26, v26
	v_mul_f32_e32 v54, v24, v24
	v_pk_add_f32 v[38:39], v[46:47], v[50:51]
	v_pk_add_f32 v[32:33], v[36:37], v[32:33]
	v_pk_fma_f32 v[48:49], v[26:27], v[26:27], v[52:53] op_sel_hi:[1,1,0]
	v_pk_fma_f32 v[52:53], v[24:25], v[24:25], v[54:55] op_sel_hi:[1,1,0]
	v_pk_add_f32 v[38:39], v[38:39], v[38:39] op_sel_hi:[0,1]
	v_pk_add_f32 v[32:33], v[32:33], v[32:33] op_sel_hi:[0,1]
	v_mul_f32_e32 v48, v30, v30
	v_mul_f32_e32 v52, v31, v31
	v_mul_f32_e32 v38, v28, v28
	v_mul_f32_e32 v32, v29, v29
	v_pk_add_f32 v[40:41], v[48:49], v[52:53]
	v_pk_add_f32 v[32:33], v[38:39], v[32:33]
	s_nop 0
	v_pk_add_f32 v[32:33], v[40:41], v[32:33]
	s_nop 0
	v_add_f32_e32 v32, v32, v33
	ds_bpermute_b32 v33, v110, v32
	s_waitcnt lgkmcnt(0)
	v_add_f32_e32 v32, v32, v33
	ds_bpermute_b32 v33, v111, v32
	s_waitcnt lgkmcnt(0)
	v_add_f32_e32 v32, v32, v33
	ds_bpermute_b32 v33, v112, v32
	s_waitcnt lgkmcnt(0)
	v_add_f32_e32 v32, v32, v33
	ds_bpermute_b32 v33, v113, v32
	s_waitcnt lgkmcnt(0)
; __device__ __forceinline__ unsigned pk2(float lo, float hi) { unsigned r; asm("v_cvt_pk_bf16_f32 %0, %1, %2" : "=v"(r) : "v"(lo), "v"(hi)); return r; }
; __device__ __forceinline__ void row_norm_store(const f32x4 (&v)[8], const float* gain, bf16_t* orow, int lane) {
;     float s = 0.f;
; #pragma unroll
;     for (int j = 0; j < 8; ++j) s += (v[j][0] * v[j][0] + v[j][1] * v[j][1]) + (v[j][2] * v[j][2] + v[j][3] * v[j][3]);
;     const float rs = 1.0f / sqrtf(wave_sum(s) * (1.0f / D_MODEL) + EPS);
; #pragma unroll
;     for (int j = 0; j < 8; ++j) { const f32x4 gv = *(const f32x4*)(gain + 4 * lane + 256 * j); const f32x4 y = v[j] * rs * gv;
;         u32x2 w; w.x = pk2(y[0], y[1]); w.y = pk2(y[2], y[3]); *(u32x2*)(orow + 4 * lane + 256 * j) = w; }
; }
	v_add_f32_e32 v32, v32, v33
	ds_bpermute_b32 v33, v114, v32
	s_waitcnt lgkmcnt(0)
	v_add_f32_e32 v32, v32, v33
	ds_bpermute_b32 v33, v115, v32
	s_waitcnt lgkmcnt(0)
	v_add_f32_e32 v32, v32, v33
	v_fmamk_f32 v32, v32, 0x3a000000, v116
	v_mul_f32_e32 v33, 0x4f800000, v32
	v_cmp_gt_f32_e32 vcc, s6, v32
	s_nop 1
	v_cndmask_b32_e32 v32, v32, v33, vcc
	v_sqrt_f32_e32 v33, v32
	s_nop 0
	v_add_u32_e32 v34, -1, v33
	v_add_u32_e32 v35, 1, v33
	v_fma_f32 v36, -v34, v33, v32
	v_fma_f32 v37, -v35, v33, v32
	v_cmp_ge_f32_e64 s[0:1], 0, v36
	s_nop 1
	v_cndmask_b32_e64 v33, v33, v34, s[0:1]
	v_cmp_lt_f32_e64 s[0:1], 0, v37
	s_nop 1
	v_cndmask_b32_e64 v33, v33, v35, s[0:1]
	v_mul_f32_e32 v34, 0x37800000, v33
	v_cndmask_b32_e32 v33, v33, v34, vcc
	v_cmp_class_f32_e32 vcc, v32, v117
	s_nop 1
	v_cndmask_b32_e32 v32, v33, v32, vcc
	v_div_scale_f32 v33, s[0:1], v32, v32, 1.0
	v_rcp_f32_e32 v35, v33
	v_div_scale_f32 v34, vcc, 1.0, v32, 1.0
	v_fma_f32 v36, -v33, v35, 1.0
	v_fmac_f32_e32 v35, v36, v35
	v_mul_f32_e32 v36, v34, v35
	v_fma_f32 v37, -v33, v36, v34
	v_fmac_f32_e32 v36, v37, v35
	v_fma_f32 v33, -v33, v36, v34
	v_div_fmas_f32 v33, v33, v35, v36
	v_div_fixup_f32 v32, v33, v32, 1.0
	v_pk_mul_f32 v[0:1], v[0:1], v[32:33] op_sel_hi:[1,0]
	v_pk_mul_f32 v[2:3], v[2:3], v[32:33] op_sel_hi:[1,0]
	s_waitcnt vmcnt(0)
	v_pk_mul_f32 v[0:1], v[64:65], v[0:1]
	v_pk_mul_f32 v[2:3], v[66:67], v[2:3]
	v_cvt_pk_bf16_f32 v0, v0, v1
	v_pk_mul_f32 v[4:5], v[4:5], v[32:33] op_sel_hi:[1,0]
	v_cvt_pk_bf16_f32 v1, v2, v3
	global_store_dwordx2 v[100:101], v[0:1], off
	v_pk_mul_f32 v[6:7], v[6:7], v[32:33] op_sel_hi:[1,0]
	v_pk_mul_f32 v[0:1], v[176:177], v[4:5]
	v_pk_mul_f32 v[2:3], v[178:179], v[6:7]
	v_cvt_pk_bf16_f32 v0, v0, v1
	v_pk_mul_f32 v[4:5], v[8:9], v[32:33] op_sel_hi:[1,0]
	v_cvt_pk_bf16_f32 v1, v2, v3
	global_store_dwordx2 v[100:101], v[0:1], off offset:512
	v_pk_mul_f32 v[6:7], v[10:11], v[32:33] op_sel_hi:[1,0]
	v_pk_mul_f32 v[0:1], v[180:181], v[4:5]
	v_pk_mul_f32 v[2:3], v[182:183], v[6:7]
	v_cvt_pk_bf16_f32 v0, v0, v1
	v_pk_mul_f32 v[4:5], v[14:15], v[32:33] op_sel_hi:[1,0]
	v_cvt_pk_bf16_f32 v1, v2, v3
	global_store_dwordx2 v[100:101], v[0:1], off offset:1024
	v_pk_mul_f32 v[6:7], v[12:13], v[32:33] op_sel_hi:[1,0]
	v_pk_mul_f32 v[0:1], v[184:185], v[4:5]
	v_pk_mul_f32 v[2:3], v[186:187], v[6:7]
	v_cvt_pk_bf16_f32 v0, v0, v1
	v_pk_mul_f32 v[4:5], v[18:19], v[32:33] op_sel_hi:[1,0]
	v_cvt_pk_bf16_f32 v1, v2, v3
	global_store_dwordx2 v[100:101], v[0:1], off offset:1536
	v_pk_mul_f32 v[6:7], v[16:17], v[32:33] op_sel_hi:[1,0]
	v_pk_mul_f32 v[0:1], v[188:189], v[4:5]
	v_pk_mul_f32 v[2:3], v[190:191], v[6:7]
	v_cvt_pk_bf16_f32 v0, v0, v1
	v_pk_mul_f32 v[4:5], v[20:21], v[32:33] op_sel_hi:[1,0]
	v_cvt_pk_bf16_f32 v1, v2, v3
	global_store_dwordx2 v[100:101], v[0:1], off offset:2048
	v_pk_mul_f32 v[6:7], v[22:23], v[32:33] op_sel_hi:[1,0]
	v_pk_mul_f32 v[0:1], v[4:5], v[192:193]
	v_pk_mul_f32 v[2:3], v[6:7], v[194:195]
	v_cvt_pk_bf16_f32 v0, v0, v1
	v_pk_mul_f32 v[4:5], v[26:27], v[32:33] op_sel_hi:[1,0]
	v_cvt_pk_bf16_f32 v1, v2, v3
	global_store_dwordx2 v[100:101], v[0:1], off offset:2560
	v_pk_mul_f32 v[6:7], v[24:25], v[32:33] op_sel_hi:[1,0]
	v_pk_mul_f32 v[0:1], v[4:5], v[196:197]
	v_pk_mul_f32 v[2:3], v[6:7], v[198:199]
	v_cvt_pk_bf16_f32 v0, v0, v1
	v_pk_mul_f32 v[4:5], v[30:31], v[32:33] op_sel_hi:[1,0]
	v_cvt_pk_bf16_f32 v1, v2, v3
	global_store_dwordx2 v[100:101], v[0:1], off offset:3072
	v_pk_mul_f32 v[6:7], v[28:29], v[32:33] op_sel_hi:[1,0]
	v_pk_mul_f32 v[0:1], v[4:5], v[200:201]
	v_pk_mul_f32 v[2:3], v[6:7], v[202:203]
	v_cvt_pk_bf16_f32 v0, v0, v1
	s_nop 0
	v_cvt_pk_bf16_f32 v1, v2, v3
	global_store_dwordx2 v[100:101], v[0:1], off offset:3584
	s_cbranch_scc1 .LBB0_451

; __device__ __forceinline__ void resid_rows(const float* prev, const bf16_t* Y, const float* ga, const bf16_t* F, const float* gc, float* xout, const float* gb, bf16_t* hn, int gw, int NGW, int lane) {
;     for (int m = gw; m < MTOK; m += NGW) {
;         f32x4 y[8]; float s = 0.f;
; #pragma unroll
;         for (int j = 0; j < 8; ++j) { const u32x2 w = *(const u32x2*)(Y + (size_t)m * LDH + 4 * lane + 256 * j); y[j] = (f32x4){bflo(w.x), bfhi(w.x), bflo(w.y), bfhi(w.y)};
;             s += (y[j][0] * y[j][0] + y[j][1] * y[j][1]) + (y[j][2] * y[j][2] + y[j][3] * y[j][3]); }
;         const float rs = 1.0f / sqrtf(wave_sum(s) * (1.0f / D_MODEL) + EPS);
;         f32x4 x1[8];
; #pragma unroll
;         for (int j = 0; j < 8; ++j) { const f32x4 pv = *(const f32x4*)(prev + (size_t)m * D_MODEL + 4 * lane + 256 * j); const f32x4 gv = *(const f32x4*)(ga + 4 * lane + 256 * j);
;             x1[j] = pv + y[j] * rs * gv; }
;         if (F) {
;             float s2 = 0.f;
; #pragma unroll
;             for (int j = 0; j < 8; ++j) { const u32x2 w = *(const u32x2*)(F + (size_t)m * LDH + 4 * lane + 256 * j); y[j] = (f32x4){bflo(w.x), bfhi(w.x), bflo(w.y), bfhi(w.y)};
;                 s2 += (y[j][0] * y[j][0] + y[j][1] * y[j][1]) + (y[j][2] * y[j][2] + y[j][3] * y[j][3]); }
;             const float rs2 = 1.0f / sqrtf(wave_sum(s2) * (1.0f / D_MODEL) + EPS);
; #pragma unroll
;             for (int j = 0; j < 8; ++j) { const f32x4 gv = *(const f32x4*)(gc + 4 * lane + 256 * j); x1[j] = x1[j] + y[j] * rs2 * gv; }
;         }
;         if (xout) {
; #pragma unroll
;             for (int j = 0; j < 8; ++j) *(f32x4*)(xout + (size_t)m * D_MODEL + 4 * lane + 256 * j) = x1[j]; }
;         if (hn) row_norm_store(x1, gb, hn + (size_t)m * LDH, lane);
;     }
; }
.LBB0_652:
	s_cmp_lt_i32 s30, 9
	s_cselect_b64 s[2:3], -1, 0
	s_and_b64 s[4:5], s[2:3], s[0:1]
	s_andn2_b64 vcc, exec, s[4:5]
	s_cbranch_vccnz .LBB0_695
	s_andn2_b64 vcc, exec, s[64:65]
	s_cbranch_vccnz .LBB0_658
	s_waitcnt vmcnt(0)
	v_mbcnt_hi_u32_b32 v0, -1, v169
	v_and_b32_e32 v1, 64, v0
	v_add_u32_e32 v1, 64, v1
	v_xor_b32_e32 v2, 1, v0
	v_cmp_lt_i32_e32 vcc, v2, v1
	v_readlane_b32 s8, v236, 2
	v_mov_b32_e32 v149, 0
	v_cndmask_b32_e32 v2, v0, v2, vcc
	v_lshlrev_b32_e32 v116, 2, v2
	v_xor_b32_e32 v2, 2, v0
	v_cmp_lt_i32_e32 vcc, v2, v1
	v_readlane_b32 s10, v236, 4
	v_readlane_b32 s11, v236, 5
	v_cndmask_b32_e32 v2, v0, v2, vcc
	v_lshlrev_b32_e32 v117, 2, v2
	v_xor_b32_e32 v2, 4, v0
	v_cmp_lt_i32_e32 vcc, v2, v1
	s_mov_b64 s[2:3], 0x8000
	s_mov_b64 s[0:1], 0x2000
	v_cndmask_b32_e32 v2, v0, v2, vcc
	v_lshlrev_b32_e32 v118, 2, v2
	v_xor_b32_e32 v2, 8, v0
	v_cmp_lt_i32_e32 vcc, v2, v1
	s_cmp_lg_u64 s[94:95], 0
	v_readlane_b32 s9, v236, 3
	v_cndmask_b32_e32 v2, v0, v2, vcc
	v_lshlrev_b32_e32 v119, 2, v2
	v_xor_b32_e32 v2, 16, v0
	v_cmp_lt_i32_e32 vcc, v2, v1
	v_readlane_b32 s12, v236, 6
	v_readlane_b32 s13, v236, 7
	v_cndmask_b32_e32 v2, v0, v2, vcc
	v_lshlrev_b32_e32 v120, 2, v2
	v_xor_b32_e32 v2, 32, v0
	v_cmp_lt_i32_e32 vcc, v2, v1
	v_readlane_b32 s14, v236, 8
	v_readlane_b32 s15, v236, 9
	v_cndmask_b32_e32 v0, v0, v2, vcc
	v_lshlrev_b32_e32 v121, 2, v0
	v_lshl_add_u64 v[0:1], s[10:11], 0, v[148:149]
	v_lshl_add_u64 v[36:37], v[0:1], 0, s[2:3]
	s_mov_b64 s[2:3], 0x9000
	v_lshl_add_u64 v[38:39], v[0:1], 0, s[2:3]
	s_mov_b64 s[2:3], 0x9400
	v_lshl_add_u64 v[40:41], v[0:1], 0, s[2:3]
	s_mov_b64 s[2:3], 0x9800
	v_lshl_add_u64 v[42:43], v[0:1], 0, s[2:3]
	s_mov_b64 s[2:3], 0x9c00
	v_lshl_add_u64 v[44:45], v[0:1], 0, s[2:3]
	s_mov_b64 s[2:3], 0x3000
	v_lshl_add_u64 v[46:47], v[0:1], 0, s[2:3]
	s_mov_b64 s[2:3], 0x3400
	v_lshl_add_u64 v[48:49], v[0:1], 0, s[2:3]
	s_mov_b64 s[2:3], 0x3800
	v_lshl_add_u64 v[50:51], v[0:1], 0, s[2:3]
	s_mov_b64 s[2:3], 0x3c00
	v_lshl_add_u64 v[52:53], v[0:1], 0, s[2:3]
	s_mov_b64 s[2:3], 0x7000
	v_lshl_add_u64 v[54:55], v[0:1], 0, s[2:3]
	s_mov_b64 s[2:3], 0x7400
	v_lshl_add_u64 v[32:33], v[0:1], 0, s[0:1]
	s_mov_b64 s[0:1], 0x6000
	v_lshl_add_u64 v[56:57], v[0:1], 0, s[2:3]
	s_mov_b64 s[2:3], 0x7800
	v_lshl_add_u64 v[34:35], v[0:1], 0, s[0:1]
	s_cselect_b64 s[0:1], -1, 0
	v_lshl_add_u64 v[58:59], v[0:1], 0, s[2:3]
	s_mov_b64 s[2:3], 0x7c00
	s_ashr_i32 s35, s34, 31
	v_lshl_add_u64 v[60:61], v[0:1], 0, s[2:3]
	s_lshl_b64 s[2:3], s[34:35], 13
	s_add_u32 s6, s8, s2
	s_addc_u32 s7, s9, s3
	s_ashr_i32 s61, s60, 31
	s_lshl_b64 s[8:9], s[60:61], 13
	v_readlane_b32 s10, v236, 19
	v_and_b32_e32 v0, 63, v168
	s_add_u32 s10, s28, s10
	v_lshlrev_b32_e32 v62, 4, v0
	v_lshlrev_b32_e32 v0, 3, v0
	v_mov_b32_e32 v1, v149
	s_addc_u32 s11, s29, s81
	v_lshl_add_u64 v[0:1], s[10:11], 0, v[0:1]
	s_mov_b64 s[10:11], 0x8000000
	v_lshl_add_u64 v[64:65], v[0:1], 0, s[10:11]
	s_add_u32 s10, s94, s2
	v_cndmask_b32_e64 v0, 0, 1, s[0:1]
	v_mov_b32_e32 v63, v149
	s_addc_u32 s11, s95, s3
	v_mov_b32_e32 v122, 0x358637bd
	s_mov_b32 s12, 0xf800000
	v_mov_b32_e32 v123, 0x260
	s_movk_i32 s13, 0x1000
	s_mov_b32 s14, 0x4400000
	v_cmp_ne_u32_e64 s[0:1], 1, v0
	s_mov_b32 s15, s34
	v_readlane_b32 s16, v236, 10
	v_readlane_b32 s17, v236, 11
	v_readlane_b32 s18, v236, 12
	v_readlane_b32 s19, v236, 13
	v_readlane_b32 s20, v236, 14
	v_readlane_b32 s21, v236, 15
	v_readlane_b32 s22, v236, 16
	v_readlane_b32 s23, v236, 17
	global_load_dwordx4 v[176:179], v[36:37], off offset:1024
	global_load_dwordx4 v[180:183], v[36:37], off offset:2048
	global_load_dwordx4 v[184:187], v[36:37], off offset:3072
	global_load_dwordx4 v[188:191], v[38:39], off
	global_load_dwordx4 v[192:195], v[40:41], off
	global_load_dwordx4 v[196:199], v[42:43], off
	global_load_dwordx4 v[200:203], v[44:45], off
	s_branch .LBB0_656
; __device__ __forceinline__ unsigned pk2(float lo, float hi) { unsigned r; asm("v_cvt_pk_bf16_f32 %0, %1, %2" : "=v"(r) : "v"(lo), "v"(hi)); return r; }
; __device__ __forceinline__ void row_norm_store(const f32x4 (&v)[8], const float* gain, bf16_t* orow, int lane) {
;     float s = 0.f;
; #pragma unroll
;     for (int j = 0; j < 8; ++j) s += (v[j][0] * v[j][0] + v[j][1] * v[j][1]) + (v[j][2] * v[j][2] + v[j][3] * v[j][3]);
;     const float rs = 1.0f / sqrtf(wave_sum(s) * (1.0f / D_MODEL) + EPS);
; #pragma unroll
;     for (int j = 0; j < 8; ++j) { const f32x4 gv = *(const f32x4*)(gain + 4 * lane + 256 * j); const f32x4 y = v[j] * rs * gv;
;         u32x2 w; w.x = pk2(y[0], y[1]); w.y = pk2(y[2], y[3]); *(u32x2*)(orow + 4 * lane + 256 * j) = w; }
; }
.LBB0_655:
	v_mov_b32_e32 v68, v29
	v_mov_b32_e32 v69, v25
	v_mov_b32_e32 v66, v28
	v_mov_b32_e32 v67, v24
	v_pk_mul_f32 v[68:69], v[68:69], v[68:69]
	v_mov_b32_e32 v70, v31
	v_mov_b32_e32 v71, v27
	v_pk_fma_f32 v[66:67], v[66:67], v[66:67], v[68:69]
	v_mov_b32_e32 v68, v30
	v_mov_b32_e32 v69, v26
	v_pk_mul_f32 v[70:71], v[70:71], v[70:71]
	s_add_i32 s15, s15, s60
	v_pk_fma_f32 v[68:69], v[68:69], v[68:69], v[70:71]
	v_pk_mul_f32 v[70:71], v[20:21], v[20:21]
	v_pk_add_f32 v[66:67], v[66:67], v[68:69]
	v_pk_mul_f32 v[68:69], v[22:23], v[22:23]
	v_pk_add_f32 v[66:67], v[66:67], v[66:67] op_sel_hi:[0,1]
	v_pk_mov_b32 v[72:73], v[70:71], v[68:69] op_sel:[1,0]
	v_mov_b32_e32 v71, v69
	v_mul_f32_e32 v66, v16, v16
	v_pk_add_f32 v[68:69], v[72:73], v[70:71]
	v_pk_fma_f32 v[70:71], v[16:17], v[16:17], v[66:67] op_sel_hi:[1,1,0]
	v_mul_f32_e32 v66, v18, v18
	v_pk_add_f32 v[68:69], v[68:69], v[68:69] op_sel_hi:[0,1]
	v_pk_fma_f32 v[72:73], v[18:19], v[18:19], v[66:67] op_sel_hi:[1,1,0]
	v_mul_f32_e32 v70, v12, v12
	v_mul_f32_e32 v72, v13, v13
	v_mul_f32_e32 v68, v14, v14
	v_mul_f32_e32 v66, v15, v15
	v_pk_add_f32 v[70:71], v[70:71], v[72:73]
	v_pk_add_f32 v[66:67], v[68:69], v[66:67]
	v_pk_mul_f32 v[68:69], v[8:9], v[8:9]
	v_pk_add_f32 v[66:67], v[70:71], v[66:67]
	s_add_u32 s6, s6, s8
	v_pk_add_f32 v[70:71], v[66:67], v[66:67] op_sel_hi:[0,1]
	v_pk_mul_f32 v[66:67], v[10:11], v[10:11]
	v_mul_f32_e32 v70, v3, v3
	v_pk_mov_b32 v[72:73], v[68:69], v[66:67] op_sel:[1,0]
	v_mov_b32_e32 v69, v67
	v_pk_add_f32 v[66:67], v[72:73], v[68:69]
	s_addc_u32 s7, s7, s9
	v_pk_add_f32 v[72:73], v[66:67], v[66:67] op_sel_hi:[0,1]
	v_mul_f32_e32 v66, v4, v4
	v_pk_fma_f32 v[74:75], v[4:5], v[4:5], v[66:67] op_sel_hi:[1,1,0]
	v_mul_f32_e32 v66, v6, v6
	v_pk_fma_f32 v[76:77], v[6:7], v[6:7], v[66:67] op_sel_hi:[1,1,0]
	global_load_dwordx4 v[66:69], v[36:37], off
	v_mul_f32_e32 v74, v0, v0
	v_mul_f32_e32 v76, v1, v1
	v_mul_f32_e32 v72, v2, v2
	v_pk_add_f32 v[74:75], v[74:75], v[76:77]
	v_pk_add_f32 v[70:71], v[72:73], v[70:71]
	s_add_u32 s10, s10, s8
	v_pk_add_f32 v[70:71], v[74:75], v[70:71]
	s_addc_u32 s11, s11, s9
	v_add_f32_e32 v70, v70, v71
	ds_bpermute_b32 v71, v116, v70
	s_cmpk_lt_i32 s15, 0x4000
	s_waitcnt lgkmcnt(0)
	v_add_f32_e32 v70, v70, v71
	ds_bpermute_b32 v71, v117, v70
	s_waitcnt lgkmcnt(0)
	v_add_f32_e32 v70, v70, v71
	ds_bpermute_b32 v71, v118, v70
	s_waitcnt lgkmcnt(0)
	v_add_f32_e32 v70, v70, v71
	ds_bpermute_b32 v71, v119, v70
	s_waitcnt lgkmcnt(0)
	v_add_f32_e32 v70, v70, v71
	ds_bpermute_b32 v71, v120, v70
	s_waitcnt lgkmcnt(0)
	v_add_f32_e32 v70, v70, v71
	ds_bpermute_b32 v71, v121, v70
	s_waitcnt lgkmcnt(0)
	v_add_f32_e32 v70, v70, v71
	v_fmamk_f32 v70, v70, 0x3a000000, v122
	v_mul_f32_e32 v71, 0x4f800000, v70
	v_cmp_gt_f32_e32 vcc, s12, v70
	s_nop 1
	v_cndmask_b32_e32 v70, v70, v71, vcc
	v_sqrt_f32_e32 v71, v70
	s_nop 0
	v_add_u32_e32 v72, -1, v71
	v_fma_f32 v73, -v72, v71, v70
	v_cmp_ge_f32_e64 s[2:3], 0, v73
	v_add_u32_e32 v73, 1, v71
	s_nop 0
	v_cndmask_b32_e64 v72, v71, v72, s[2:3]
	v_fma_f32 v71, -v73, v71, v70
	v_cmp_lt_f32_e64 s[2:3], 0, v71
	s_nop 1
	v_cndmask_b32_e64 v71, v72, v73, s[2:3]
	v_mul_f32_e32 v72, 0x37800000, v71
	v_cndmask_b32_e32 v71, v71, v72, vcc
	v_cmp_class_f32_e32 vcc, v70, v123
	s_nop 1
	v_cndmask_b32_e32 v70, v71, v70, vcc
	v_div_scale_f32 v71, s[2:3], v70, v70, 1.0
	v_rcp_f32_e32 v72, v71
	s_nop 0
	v_fma_f32 v73, -v71, v72, 1.0
	v_fmac_f32_e32 v72, v73, v72
	v_div_scale_f32 v73, vcc, 1.0, v70, 1.0
	v_mul_f32_e32 v74, v73, v72
	v_fma_f32 v75, -v71, v74, v73
	v_fmac_f32_e32 v74, v75, v72
	v_fma_f32 v71, -v71, v74, v73
	v_div_fmas_f32 v71, v71, v72, v74
	v_div_fixup_f32 v70, v71, v70, 1.0
	v_pk_mul_f32 v[28:29], v[28:29], v[70:71] op_sel_hi:[1,0]
	v_pk_mul_f32 v[30:31], v[30:31], v[70:71] op_sel_hi:[1,0]
	s_waitcnt vmcnt(0)
	v_pk_mul_f32 v[28:29], v[66:67], v[28:29]
	v_pk_mul_f32 v[30:31], v[68:69], v[30:31]
	v_cvt_pk_bf16_f32 v28, v28, v29
	v_pk_mul_f32 v[24:25], v[24:25], v[70:71] op_sel_hi:[1,0]
	v_cvt_pk_bf16_f32 v29, v30, v31
	global_store_dwordx2 v[64:65], v[28:29], off
	v_pk_mul_f32 v[26:27], v[26:27], v[70:71] op_sel_hi:[1,0]
	v_pk_mul_f32 v[20:21], v[20:21], v[70:71] op_sel_hi:[1,0]
	v_pk_mul_f32 v[22:23], v[22:23], v[70:71] op_sel_hi:[1,0]
	v_pk_mul_f32 v[16:17], v[16:17], v[70:71] op_sel_hi:[1,0]
	v_pk_mul_f32 v[18:19], v[18:19], v[70:71] op_sel_hi:[1,0]
	v_pk_mul_f32 v[12:13], v[12:13], v[70:71] op_sel_hi:[1,0]
	v_pk_mul_f32 v[14:15], v[14:15], v[70:71] op_sel_hi:[1,0]
	v_pk_mul_f32 v[8:9], v[8:9], v[70:71] op_sel_hi:[1,0]
	v_pk_mul_f32 v[10:11], v[10:11], v[70:71] op_sel_hi:[1,0]
	v_pk_mul_f32 v[4:5], v[4:5], v[70:71] op_sel_hi:[1,0]
	v_pk_mul_f32 v[6:7], v[6:7], v[70:71] op_sel_hi:[1,0]
	v_pk_mul_f32 v[0:1], v[0:1], v[70:71] op_sel_hi:[1,0]
	v_pk_mul_f32 v[2:3], v[2:3], v[70:71] op_sel_hi:[1,0]
	v_pk_mul_f32 v[24:25], v[176:177], v[24:25]
	v_pk_mul_f32 v[26:27], v[178:179], v[26:27]
	v_cvt_pk_bf16_f32 v24, v24, v25
	s_nop 0
	v_cvt_pk_bf16_f32 v25, v26, v27
	global_store_dwordx2 v[64:65], v[24:25], off offset:512
	v_pk_mul_f32 v[20:21], v[180:181], v[20:21]
	v_pk_mul_f32 v[22:23], v[182:183], v[22:23]
	v_cvt_pk_bf16_f32 v20, v20, v21
	s_nop 0
	v_cvt_pk_bf16_f32 v21, v22, v23
	global_store_dwordx2 v[64:65], v[20:21], off offset:1024
	v_pk_mul_f32 v[16:17], v[16:17], v[184:185]
	v_pk_mul_f32 v[18:19], v[18:19], v[186:187]
	v_cvt_pk_bf16_f32 v16, v16, v17
	s_nop 0
	v_cvt_pk_bf16_f32 v17, v18, v19
	global_store_dwordx2 v[64:65], v[16:17], off offset:1536
	v_pk_mul_f32 v[12:13], v[12:13], v[188:189]
	v_pk_mul_f32 v[14:15], v[14:15], v[190:191]
	v_cvt_pk_bf16_f32 v12, v12, v13
	s_nop 0
	v_cvt_pk_bf16_f32 v13, v14, v15
	global_store_dwordx2 v[64:65], v[12:13], off offset:2048
	v_pk_mul_f32 v[8:9], v[8:9], v[192:193]
	v_pk_mul_f32 v[10:11], v[10:11], v[194:195]
	v_cvt_pk_bf16_f32 v8, v8, v9
	s_nop 0
	v_cvt_pk_bf16_f32 v9, v10, v11
	global_store_dwordx2 v[64:65], v[8:9], off offset:2560
	v_pk_mul_f32 v[4:5], v[4:5], v[196:197]
	v_pk_mul_f32 v[6:7], v[6:7], v[198:199]
	v_cvt_pk_bf16_f32 v4, v4, v5
	s_nop 0
	v_cvt_pk_bf16_f32 v5, v6, v7
	global_store_dwordx2 v[64:65], v[4:5], off offset:3072
	v_pk_mul_f32 v[0:1], v[0:1], v[200:201]
	v_pk_mul_f32 v[2:3], v[2:3], v[202:203]
	v_cvt_pk_bf16_f32 v0, v0, v1
	s_nop 0
	v_cvt_pk_bf16_f32 v1, v2, v3
	global_store_dwordx2 v[64:65], v[0:1], off offset:3584
	v_lshl_add_u64 v[64:65], v[64:65], 0, s[82:83]
	s_cbranch_scc0 .LBB0_658

; __device__ __forceinline__ void resid_rows(const float* prev, const bf16_t* Y, const float* ga, const bf16_t* F, const float* gc, float* xout, const float* gb, bf16_t* hn, int gw, int NGW, int lane) {
;     for (int m = gw; m < MTOK; m += NGW) {
;         f32x4 y[8]; float s = 0.f;
; #pragma unroll
;         for (int j = 0; j < 8; ++j) { const u32x2 w = *(const u32x2*)(Y + (size_t)m * LDH + 4 * lane + 256 * j); y[j] = (f32x4){bflo(w.x), bfhi(w.x), bflo(w.y), bfhi(w.y)};
;             s += (y[j][0] * y[j][0] + y[j][1] * y[j][1]) + (y[j][2] * y[j][2] + y[j][3] * y[j][3]); }
;         const float rs = 1.0f / sqrtf(wave_sum(s) * (1.0f / D_MODEL) + EPS);
;         f32x4 x1[8];
; #pragma unroll
;         for (int j = 0; j < 8; ++j) { const f32x4 pv = *(const f32x4*)(prev + (size_t)m * D_MODEL + 4 * lane + 256 * j); const f32x4 gv = *(const f32x4*)(ga + 4 * lane + 256 * j);
;             x1[j] = pv + y[j] * rs * gv; }
.LBB0_1089:
	s_cmp_lt_i32 s30, 13
	s_cselect_b64 s[2:3], -1, 0
	s_and_b64 s[2:3], s[2:3], s[0:1]
	s_and_b64 s[0:1], s[2:3], s[64:65]
	s_andn2_b64 vcc, exec, s[0:1]
	s_cbranch_vccnz .LBB0_1092
	s_waitcnt vmcnt(0)
	v_mbcnt_hi_u32_b32 v0, -1, v169
	s_waitcnt lgkmcnt(0)
	v_and_b32_e32 v1, 64, v0
	v_add_u32_e32 v1, 64, v1
	v_xor_b32_e32 v2, 1, v0
	v_cmp_lt_i32_e32 vcc, v2, v1
	v_readlane_b32 s4, v236, 2
	v_mov_b32_e32 v149, 0
	v_cndmask_b32_e32 v2, v0, v2, vcc
	v_lshlrev_b32_e32 v110, 2, v2
	v_xor_b32_e32 v2, 2, v0
	v_cmp_lt_i32_e32 vcc, v2, v1
	v_readlane_b32 s6, v236, 4
	v_readlane_b32 s7, v236, 5
	v_cndmask_b32_e32 v2, v0, v2, vcc
	v_lshlrev_b32_e32 v111, 2, v2
	v_xor_b32_e32 v2, 4, v0
	v_cmp_lt_i32_e32 vcc, v2, v1
	s_mov_b64 s[0:1], 0xa000
	s_ashr_i32 s35, s34, 31
	v_cndmask_b32_e32 v2, v0, v2, vcc
	v_lshlrev_b32_e32 v112, 2, v2
	v_xor_b32_e32 v2, 8, v0
	v_cmp_lt_i32_e32 vcc, v2, v1
	v_readlane_b32 s5, v236, 3
	v_readlane_b32 s8, v236, 6
	v_cndmask_b32_e32 v2, v0, v2, vcc
	v_lshlrev_b32_e32 v113, 2, v2
	v_xor_b32_e32 v2, 16, v0
	v_cmp_lt_i32_e32 vcc, v2, v1
	v_mov_b32_e32 v116, 0x358637bd
	v_mov_b32_e32 v117, 0x260
	v_cndmask_b32_e32 v2, v0, v2, vcc
	v_lshlrev_b32_e32 v114, 2, v2
	v_xor_b32_e32 v2, 32, v0
	v_cmp_lt_i32_e32 vcc, v2, v1
	s_mov_b32 s8, s34
	v_readlane_b32 s9, v236, 7
	v_cndmask_b32_e32 v0, v0, v2, vcc
	v_lshlrev_b32_e32 v115, 2, v0
	v_lshl_add_u64 v[0:1], s[6:7], 0, v[148:149]
	v_lshl_add_u64 v[68:69], v[0:1], 0, s[0:1]
	s_mov_b64 s[0:1], 0xc000
	v_lshl_add_u64 v[70:71], v[0:1], 0, s[0:1]
	s_mov_b64 s[0:1], 0xd000
	v_lshl_add_u64 v[72:73], v[0:1], 0, s[0:1]
	s_mov_b64 s[0:1], 0xd400
	v_lshl_add_u64 v[74:75], v[0:1], 0, s[0:1]
	s_mov_b64 s[0:1], 0xd800
	v_lshl_add_u64 v[76:77], v[0:1], 0, s[0:1]
	s_mov_b64 s[0:1], 0xdc00
	v_lshl_add_u64 v[78:79], v[0:1], 0, s[0:1]
	s_mov_b64 s[0:1], 0xb000
	v_lshl_add_u64 v[80:81], v[0:1], 0, s[0:1]
	s_mov_b64 s[0:1], 0xb400
	v_lshl_add_u64 v[82:83], v[0:1], 0, s[0:1]
	s_mov_b64 s[0:1], 0xb800
	v_lshl_add_u64 v[84:85], v[0:1], 0, s[0:1]
	s_mov_b64 s[0:1], 0xbc00
	v_lshl_add_u64 v[86:87], v[0:1], 0, s[0:1]
	s_lshl_b64 s[0:1], s[34:35], 13
	v_and_b32_e32 v2, 63, v168
	s_add_u32 s0, s94, s0
	v_lshlrev_b32_e32 v0, 4, v2
	v_mov_b32_e32 v1, v149
	s_addc_u32 s1, s95, s1
	v_lshl_add_u64 v[0:1], s[0:1], 0, v[0:1]
	s_mov_b64 s[0:1], 0x1000
	s_ashr_i32 s61, s60, 31
	v_lshl_add_u64 v[88:89], v[0:1], 0, s[0:1]
	s_lshl_b64 s[4:5], s[60:61], 13
	v_readlane_b32 s0, v236, 19
	s_add_u32 s0, s28, s0
	v_lshlrev_b32_e32 v0, 3, v2
	v_mov_b32_e32 v1, v149
	s_addc_u32 s1, s29, s81
	v_lshl_add_u64 v[0:1], s[0:1], 0, v[0:1]
	s_mov_b64 s[0:1], 0x8000000
	v_lshl_add_u64 v[90:91], v[0:1], 0, s[0:1]
	s_mov_b32 s6, 0xf800000
	s_mov_b32 s7, 0x4400000
	v_readlane_b32 s10, v236, 8
	v_readlane_b32 s11, v236, 9
	v_readlane_b32 s12, v236, 10
	v_readlane_b32 s13, v236, 11
	v_readlane_b32 s14, v236, 12
	v_readlane_b32 s15, v236, 13
	v_readlane_b32 s16, v236, 14
	v_readlane_b32 s17, v236, 15
	v_readlane_b32 s18, v236, 16
	v_readlane_b32 s19, v236, 17
	global_load_dwordx4 v[176:179], v[70:71], off offset:1024
	global_load_dwordx4 v[180:183], v[70:71], off offset:2048
	global_load_dwordx4 v[184:187], v[70:71], off offset:3072
	global_load_dwordx4 v[188:191], v[72:73], off
	global_load_dwordx4 v[192:195], v[74:75], off
	global_load_dwordx4 v[196:199], v[76:77], off
	global_load_dwordx4 v[200:203], v[78:79], off
.LBB0_1091:
	global_load_dwordx2 v[92:93], v[90:91], off
	global_load_dwordx2 v[94:95], v[90:91], off offset:512
	global_load_dwordx2 v[96:97], v[90:91], off offset:1024
	global_load_dwordx2 v[98:99], v[90:91], off offset:1536
	global_load_dwordx2 v[102:103], v[90:91], off offset:2048
	global_load_dwordx2 v[104:105], v[90:91], off offset:2560
	global_load_dwordx2 v[106:107], v[90:91], off offset:3072
	global_load_dwordx2 v[108:109], v[90:91], off offset:3584
	global_load_dwordx4 v[0:3], v[88:89], off offset:-4096
	global_load_dwordx4 v[4:7], v[88:89], off offset:-3072
	global_load_dwordx4 v[12:15], v[68:69], off
	global_load_dwordx4 v[8:11], v[68:69], off offset:1024
	global_load_dwordx4 v[16:19], v[88:89], off offset:-2048
	global_load_dwordx4 v[20:23], v[88:89], off offset:-1024
	global_load_dwordx4 v[28:31], v[68:69], off offset:2048
	global_load_dwordx4 v[24:27], v[68:69], off offset:3072
	global_load_dwordx4 v[32:35], v[88:89], off
	global_load_dwordx4 v[36:39], v[88:89], off offset:1024
	global_load_dwordx4 v[40:43], v[82:83], off
	global_load_dwordx4 v[44:47], v[84:85], off
	global_load_dwordx4 v[48:51], v[88:89], off offset:2048
	global_load_dwordx4 v[52:55], v[88:89], off offset:3072
	global_load_dwordx4 v[56:59], v[86:87], off
	global_load_dwordx4 v[60:63], v[80:81], off
	global_load_dwordx4 v[64:67], v[70:71], off
	v_add_co_u32_e32 v100, vcc, s7, v90
	s_add_i32 s8, s8, s60
	s_nop 0
	v_addc_co_u32_e32 v101, vcc, 0, v91, vcc
	v_lshl_add_u64 v[88:89], v[88:89], 0, s[4:5]
	v_lshl_add_u64 v[90:91], v[90:91], 0, s[82:83]
	s_cmpk_lt_i32 s8, 0x4000
	s_waitcnt vmcnt(24)
	v_lshlrev_b32_e32 v118, 16, v92
	v_and_b32_e32 v119, 0xffff0000, v92
	v_lshlrev_b32_e32 v92, 16, v93
	v_and_b32_e32 v93, 0xffff0000, v93
	s_waitcnt vmcnt(23)
	v_lshlrev_b32_e32 v121, 16, v95
	v_lshlrev_b32_e32 v120, 16, v94
	v_and_b32_e32 v95, 0xffff0000, v95
	v_and_b32_e32 v94, 0xffff0000, v94
	s_waitcnt vmcnt(22)
	v_and_b32_e32 v123, 0xffff0000, v96
	s_waitcnt vmcnt(21)
	v_lshlrev_b32_e32 v125, 16, v98
	s_waitcnt vmcnt(17)
; __device__ __forceinline__ void resid_rows(const float* prev, const bf16_t* Y, const float* ga, const bf16_t* F, const float* gc, float* xout, const float* gb, bf16_t* hn, int gw, int NGW, int lane) {
;     ...
;         for (int j = 0; j < 8; ++j) { const u32x2 w = *(const u32x2*)(Y + (size_t)m * LDH + 4 * lane + 256 * j); y[j] = (f32x4){bflo(w.x), bfhi(w.x), bflo(w.y), bfhi(w.y)};
;             s += (y[j][0] * y[j][0] + y[j][1] * y[j][1]) + (y[j][2] * y[j][2] + y[j][3] * y[j][3]); }
;         const float rs = 1.0f / sqrtf(wave_sum(s) * (1.0f / D_MODEL) + EPS);
	v_lshlrev_b32_e32 v135, 16, v108
	v_mul_f32_e32 v124, v93, v93
	v_pk_mul_f32 v[138:139], v[94:95], v[94:95]
	v_mul_f32_e32 v134, v119, v119
	v_lshlrev_b32_e32 v122, 16, v96
	v_lshlrev_b32_e32 v96, 16, v97
	v_and_b32_e32 v97, 0xffff0000, v97
	v_lshlrev_b32_e32 v129, 16, v103
	v_lshlrev_b32_e32 v128, 16, v102
	v_and_b32_e32 v103, 0xffff0000, v103
	v_and_b32_e32 v102, 0xffff0000, v102
	v_lshlrev_b32_e32 v131, 16, v105
	v_lshlrev_b32_e32 v130, 16, v104
	v_and_b32_e32 v105, 0xffff0000, v105
	v_and_b32_e32 v104, 0xffff0000, v104
	v_mov_b32_e32 v141, v125
	v_mul_f32_e32 v140, v123, v123
	v_mov_b32_e32 v154, v120
	v_mov_b32_e32 v155, v94
	v_mov_b32_e32 v94, v121
	v_pk_fma_f32 v[160:161], v[92:93], v[92:93], v[124:125] op_sel_hi:[1,1,0]
	v_pk_fma_f32 v[120:121], v[120:121], v[120:121], v[138:139]
	v_pk_fma_f32 v[138:139], v[118:119], v[118:119], v[134:135] op_sel_hi:[1,1,0]
	v_and_b32_e32 v127, 0xffff0000, v98
	v_lshlrev_b32_e32 v98, 16, v99
	v_and_b32_e32 v99, 0xffff0000, v99
	v_mul_f32_e32 v142, v97, v97
	v_pk_mul_f32 v[144:145], v[102:103], v[102:103]
	v_pk_mul_f32 v[146:147], v[104:105], v[104:105]
	v_mov_b32_e32 v143, v135
	v_pk_fma_f32 v[162:163], v[122:123], v[122:123], v[140:141] op_sel_hi:[1,1,0]
	v_mov_b32_e32 v124, v138
	v_mov_b32_e32 v140, v160
	v_mul_f32_e32 v149, v127, v127
	v_mul_f32_e32 v153, v98, v98
	v_mul_f32_e32 v166, v99, v99
	v_mov_b32_e32 v126, v125
	v_mov_b32_e32 v156, v128
	v_mov_b32_e32 v157, v102
	v_mov_b32_e32 v102, v129
	v_mov_b32_e32 v158, v131
	v_mov_b32_e32 v159, v105
	v_pk_fma_f32 v[164:165], v[96:97], v[96:97], v[142:143] op_sel_hi:[1,1,0]
	v_pk_fma_f32 v[128:129], v[128:129], v[128:129], v[144:145]
	v_pk_fma_f32 v[144:145], v[130:131], v[130:131], v[146:147]
	v_mov_b32_e32 v131, v104
	v_pk_add_f32 v[104:105], v[138:139], v[160:161]
	v_pk_add_f32 v[120:121], v[120:121], v[120:121] op_sel:[0,1] op_sel_hi:[1,0]
	v_pk_mul_f32 v[124:125], v[124:125], v[140:141]
	v_mov_b32_e32 v163, v153
	v_mov_b32_e32 v165, v166
	v_mov_b32_e32 v121, v149
	v_mov_b32_e32 v105, v125
	v_pk_add_f32 v[140:141], v[162:163], v[164:165]
	v_pk_add_f32 v[104:105], v[104:105], v[120:121]
	v_lshlrev_b32_e32 v132, 16, v106
	v_pk_add_f32 v[104:105], v[104:105], v[140:141]
	v_and_b32_e32 v133, 0xffff0000, v106
	v_lshlrev_b32_e32 v106, 16, v107
	v_and_b32_e32 v107, 0xffff0000, v107
	v_pk_add_f32 v[128:129], v[128:129], v[128:129] op_sel:[0,1] op_sel_hi:[1,0]
	v_pk_add_f32 v[104:105], v[104:105], v[104:105] op_sel:[0,1] op_sel_hi:[1,0]
	v_and_b32_e32 v137, 0xffff0000, v108
	v_lshlrev_b32_e32 v108, 16, v109
	v_and_b32_e32 v109, 0xffff0000, v109
	v_mul_f32_e32 v150, v133, v133
	v_mul_f32_e32 v152, v107, v107
	v_mov_b32_e32 v142, v128
	v_mov_b32_e32 v134, v104
	v_mul_f32_e32 v167, v137, v137
	v_mul_f32_e32 v170, v108, v108
	v_mul_f32_e32 v171, v109, v109
	v_pk_fma_f32 v[146:147], v[132:133], v[132:133], v[150:151] op_sel_hi:[1,1,0]
	v_pk_fma_f32 v[150:151], v[106:107], v[106:107], v[152:153] op_sel_hi:[1,1,0]
	v_pk_add_f32 v[138:139], v[144:145], v[144:145] op_sel:[0,1] op_sel_hi:[1,0]
	v_pk_add_f32 v[104:105], v[104:105], v[128:129]
	v_pk_mul_f32 v[120:121], v[134:135], v[142:143]
	v_mov_b32_e32 v147, v170
	v_mov_b32_e32 v151, v171
	v_mov_b32_e32 v139, v167
	v_mov_b32_e32 v105, v121
	v_pk_add_f32 v[144:145], v[146:147], v[150:151]
	v_pk_add_f32 v[104:105], v[104:105], v[138:139]
	v_mov_b32_e32 v136, v135
	v_pk_add_f32 v[104:105], v[104:105], v[144:145]
	s_nop 0
	v_add_f32_e32 v104, v104, v105
	ds_bpermute_b32 v105, v110, v104
	s_waitcnt lgkmcnt(0)
	v_add_f32_e32 v104, v104, v105
	ds_bpermute_b32 v105, v111, v104
	s_waitcnt lgkmcnt(0)
	v_add_f32_e32 v104, v104, v105
	ds_bpermute_b32 v105, v112, v104
	s_waitcnt lgkmcnt(0)
	v_add_f32_e32 v104, v104, v105
	ds_bpermute_b32 v105, v113, v104
	s_waitcnt lgkmcnt(0)
	v_add_f32_e32 v104, v104, v105
	ds_bpermute_b32 v105, v114, v104
	s_waitcnt lgkmcnt(0)
	v_add_f32_e32 v104, v104, v105
	ds_bpermute_b32 v105, v115, v104
	s_waitcnt lgkmcnt(0)
	v_add_f32_e32 v104, v104, v105
	v_fmamk_f32 v104, v104, 0x3a000000, v116
	v_mul_f32_e32 v105, 0x4f800000, v104
	v_cmp_gt_f32_e32 vcc, s6, v104
	s_nop 1
	v_cndmask_b32_e32 v104, v104, v105, vcc
	v_sqrt_f32_e32 v105, v104
	s_nop 0
	v_add_u32_e32 v120, -1, v105
	v_add_u32_e32 v121, 1, v105
	v_fma_f32 v124, -v120, v105, v104
	v_fma_f32 v125, -v121, v105, v104
	v_cmp_ge_f32_e64 s[0:1], 0, v124
	s_nop 1
	v_cndmask_b32_e64 v105, v105, v120, s[0:1]
	v_cmp_lt_f32_e64 s[0:1], 0, v125
	s_nop 1
	v_cndmask_b32_e64 v105, v105, v121, s[0:1]
	v_mul_f32_e32 v120, 0x37800000, v105
	v_cndmask_b32_e32 v105, v105, v120, vcc
	v_cmp_class_f32_e32 vcc, v104, v117
	s_nop 1
	v_cndmask_b32_e32 v104, v105, v104, vcc
	v_div_scale_f32 v105, s[0:1], v104, v104, 1.0
	v_rcp_f32_e32 v121, v105
	v_div_scale_f32 v120, vcc, 1.0, v104, 1.0
	v_fma_f32 v124, -v105, v121, 1.0
	v_fmac_f32_e32 v121, v124, v121
	v_mul_f32_e32 v124, v120, v121
	v_fma_f32 v125, -v105, v124, v120
	v_fmac_f32_e32 v124, v125, v121
	v_fma_f32 v105, -v105, v124, v120
	v_div_fmas_f32 v105, v105, v121, v124
	v_div_fixup_f32 v104, v105, v104, 1.0
	v_pk_mul_f32 v[118:119], v[104:105], v[118:119] op_sel_hi:[0,1]
	v_pk_mul_f32 v[92:93], v[104:105], v[92:93] op_sel_hi:[0,1]
	v_pk_mul_f32 v[120:121], v[104:105], v[154:155] op_sel_hi:[0,1]
	v_pk_mul_f32 v[94:95], v[104:105], v[94:95] op_sel_hi:[0,1]
	v_pk_mul_f32 v[96:97], v[104:105], v[96:97] op_sel_hi:[0,1]
	v_pk_mul_f32 v[122:123], v[104:105], v[122:123] op_sel_hi:[0,1]
	v_pk_mul_f32 v[98:99], v[98:99], v[104:105] op_sel_hi:[1,0]
	v_pk_mul_f32 v[102:103], v[104:105], v[102:103] op_sel_hi:[0,1]
	v_pk_mul_f32 v[128:129], v[104:105], v[158:159] op_sel_hi:[0,1]
	s_waitcnt vmcnt(14)
; __device__ __forceinline__ void row_norm_store(const f32x4 (&v)[8], const float* gain, bf16_t* orow, int lane) {
;     float s = 0.f;
; #pragma unroll
;     for (int j = 0; j < 8; ++j) s += (v[j][0] * v[j][0] + v[j][1] * v[j][1]) + (v[j][2] * v[j][2] + v[j][3] * v[j][3]);
; __device__ __forceinline__ void resid_rows(const float* prev, const bf16_t* Y, const float* ga, const bf16_t* F, const float* gc, float* xout, const float* gb, bf16_t* hn, int gw, int NGW, int lane) {
;     ...
;         f32x4 x1[8];
; #pragma unroll
;         for (int j = 0; j < 8; ++j) { const f32x4 pv = *(const f32x4*)(prev + (size_t)m * D_MODEL + 4 * lane + 256 * j); const f32x4 gv = *(const f32x4*)(ga + 4 * lane + 256 * j);
;             x1[j] = pv + y[j] * rs * gv; }
	v_pk_fma_f32 v[2:3], v[14:15], v[92:93], v[2:3]
	v_pk_fma_f32 v[0:1], v[12:13], v[118:119], v[0:1]
	s_waitcnt vmcnt(13)
	v_pk_fma_f32 v[6:7], v[10:11], v[94:95], v[6:7]
	v_pk_fma_f32 v[4:5], v[8:9], v[120:121], v[4:5]
	v_pk_mul_f32 v[124:125], v[126:127], v[104:105] op_sel_hi:[1,0]
	v_pk_mul_f32 v[126:127], v[104:105], v[156:157] op_sel_hi:[0,1]
	v_pk_mul_f32 v[130:131], v[104:105], v[130:131] op_sel_hi:[0,1]
	s_waitcnt vmcnt(10)
	v_pk_fma_f32 v[8:9], v[28:29], v[122:123], v[16:17]
	v_pk_fma_f32 v[10:11], v[30:31], v[96:97], v[18:19]
	s_waitcnt vmcnt(9)
	v_pk_fma_f32 v[12:13], v[26:27], v[98:99], v[22:23]
	s_waitcnt vmcnt(1)
	v_pk_fma_f32 v[16:17], v[62:63], v[102:103], v[34:35]
	v_pk_fma_f32 v[22:23], v[42:43], v[128:129], v[38:39]
	v_mov_b32_e32 v34, v1
	v_mov_b32_e32 v35, v5
	v_mov_b32_e32 v38, v3
	v_mov_b32_e32 v39, v7
	v_pk_mul_f32 v[134:135], v[136:137], v[104:105] op_sel_hi:[1,0]
	v_pk_fma_f32 v[14:15], v[24:25], v[124:125], v[20:21]
	v_pk_fma_f32 v[18:19], v[60:61], v[126:127], v[32:33]
	v_pk_fma_f32 v[20:21], v[40:41], v[130:131], v[36:37]
	v_mov_b32_e32 v32, v0
	v_mov_b32_e32 v33, v4
	v_mov_b32_e32 v36, v2
	v_mov_b32_e32 v37, v6
	v_pk_mul_f32 v[40:41], v[10:11], v[10:11]
	v_pk_mul_f32 v[42:43], v[8:9], v[8:9]
	v_pk_mul_f32 v[34:35], v[34:35], v[34:35]
	v_pk_mul_f32 v[38:39], v[38:39], v[38:39]
	v_pk_mul_f32 v[132:133], v[104:105], v[132:133] op_sel_hi:[0,1]
	v_pk_mul_f32 v[106:107], v[104:105], v[106:107] op_sel_hi:[0,1]
	v_pk_fma_f32 v[30:31], v[134:135], v[56:57], v[52:53]
	v_pk_mov_b32 v[56:57], v[42:43], v[40:41] op_sel:[1,0]
	v_mov_b32_e32 v43, v41
	v_pk_fma_f32 v[32:33], v[32:33], v[32:33], v[34:35]
	v_pk_fma_f32 v[34:35], v[36:37], v[36:37], v[38:39]
	v_pk_fma_f32 v[24:25], v[46:47], v[106:107], v[50:51]
	v_pk_fma_f32 v[26:27], v[44:45], v[132:133], v[48:49]
	v_mul_f32_e32 v44, v14, v14
	v_mul_f32_e32 v46, v12, v12
	v_pk_add_f32 v[36:37], v[56:57], v[42:43]
	v_pk_add_f32 v[32:33], v[32:33], v[34:35]
	v_pk_fma_f32 v[40:41], v[14:15], v[14:15], v[44:45] op_sel_hi:[1,1,0]
	v_pk_fma_f32 v[44:45], v[12:13], v[12:13], v[46:47] op_sel_hi:[1,1,0]
	v_pk_add_f32 v[34:35], v[36:37], v[36:37] op_sel_hi:[0,1]
	v_pk_add_f32 v[32:33], v[32:33], v[32:33] op_sel_hi:[0,1]
	v_pk_mul_f32 v[48:49], v[22:23], v[22:23]
	v_pk_mul_f32 v[50:51], v[20:21], v[20:21]
	v_mul_f32_e32 v40, v18, v18
	v_mul_f32_e32 v44, v19, v19
	v_mul_f32_e32 v34, v16, v16
	v_mul_f32_e32 v32, v17, v17
	v_pk_mul_f32 v[104:105], v[108:109], v[104:105] op_sel_hi:[1,0]
	v_pk_mov_b32 v[46:47], v[50:51], v[48:49] op_sel:[1,0]
	v_mov_b32_e32 v51, v49
	v_pk_add_f32 v[36:37], v[40:41], v[44:45]
	v_pk_add_f32 v[32:33], v[34:35], v[32:33]
	v_pk_fma_f32 v[28:29], v[104:105], v[58:59], v[54:55]
	v_mul_f32_e32 v52, v26, v26
	v_mul_f32_e32 v54, v24, v24
	v_pk_add_f32 v[38:39], v[46:47], v[50:51]
	v_pk_add_f32 v[32:33], v[36:37], v[32:33]
	v_pk_fma_f32 v[48:49], v[26:27], v[26:27], v[52:53] op_sel_hi:[1,1,0]
	v_pk_fma_f32 v[52:53], v[24:25], v[24:25], v[54:55] op_sel_hi:[1,1,0]
	v_pk_add_f32 v[38:39], v[38:39], v[38:39] op_sel_hi:[0,1]
	v_pk_add_f32 v[32:33], v[32:33], v[32:33] op_sel_hi:[0,1]
	v_mul_f32_e32 v48, v30, v30
	v_mul_f32_e32 v52, v31, v31
	v_mul_f32_e32 v38, v28, v28
	v_mul_f32_e32 v32, v29, v29
	v_pk_add_f32 v[40:41], v[48:49], v[52:53]
	v_pk_add_f32 v[32:33], v[38:39], v[32:33]
	s_nop 0
	v_pk_add_f32 v[32:33], v[40:41], v[32:33]
	s_nop 0
	v_add_f32_e32 v32, v32, v33
	ds_bpermute_b32 v33, v110, v32
	s_waitcnt lgkmcnt(0)
	v_add_f32_e32 v32, v32, v33
	ds_bpermute_b32 v33, v111, v32
	s_waitcnt lgkmcnt(0)
	v_add_f32_e32 v32, v32, v33
	ds_bpermute_b32 v33, v112, v32
	s_waitcnt lgkmcnt(0)
	v_add_f32_e32 v32, v32, v33
	ds_bpermute_b32 v33, v113, v32
	s_waitcnt lgkmcnt(0)
; __device__ __forceinline__ unsigned pk2(float lo, float hi) { unsigned r; asm("v_cvt_pk_bf16_f32 %0, %1, %2" : "=v"(r) : "v"(lo), "v"(hi)); return r; }
; __device__ __forceinline__ void row_norm_store(const f32x4 (&v)[8], const float* gain, bf16_t* orow, int lane) {
;     float s = 0.f;
; #pragma unroll
;     for (int j = 0; j < 8; ++j) s += (v[j][0] * v[j][0] + v[j][1] * v[j][1]) + (v[j][2] * v[j][2] + v[j][3] * v[j][3]);
;     const float rs = 1.0f / sqrtf(wave_sum(s) * (1.0f / D_MODEL) + EPS);
; #pragma unroll
;     for (int j = 0; j < 8; ++j) { const f32x4 gv = *(const f32x4*)(gain + 4 * lane + 256 * j); const f32x4 y = v[j] * rs * gv;
;         u32x2 w; w.x = pk2(y[0], y[1]); w.y = pk2(y[2], y[3]); *(u32x2*)(orow + 4 * lane + 256 * j) = w; }
; }
	v_add_f32_e32 v32, v32, v33
	ds_bpermute_b32 v33, v114, v32
	s_waitcnt lgkmcnt(0)
	v_add_f32_e32 v32, v32, v33
	ds_bpermute_b32 v33, v115, v32
	s_waitcnt lgkmcnt(0)
	v_add_f32_e32 v32, v32, v33
	v_fmamk_f32 v32, v32, 0x3a000000, v116
	v_mul_f32_e32 v33, 0x4f800000, v32
	v_cmp_gt_f32_e32 vcc, s6, v32
	s_nop 1
	v_cndmask_b32_e32 v32, v32, v33, vcc
	v_sqrt_f32_e32 v33, v32
	s_nop 0
	v_add_u32_e32 v34, -1, v33
	v_add_u32_e32 v35, 1, v33
	v_fma_f32 v36, -v34, v33, v32
	v_fma_f32 v37, -v35, v33, v32
	v_cmp_ge_f32_e64 s[0:1], 0, v36
	s_nop 1
	v_cndmask_b32_e64 v33, v33, v34, s[0:1]
	v_cmp_lt_f32_e64 s[0:1], 0, v37
	s_nop 1
	v_cndmask_b32_e64 v33, v33, v35, s[0:1]
	v_mul_f32_e32 v34, 0x37800000, v33
	v_cndmask_b32_e32 v33, v33, v34, vcc
	v_cmp_class_f32_e32 vcc, v32, v117
	s_nop 1
	v_cndmask_b32_e32 v32, v33, v32, vcc
	v_div_scale_f32 v33, s[0:1], v32, v32, 1.0
	v_rcp_f32_e32 v35, v33
	v_div_scale_f32 v34, vcc, 1.0, v32, 1.0
	v_fma_f32 v36, -v33, v35, 1.0
	v_fmac_f32_e32 v35, v36, v35
	v_mul_f32_e32 v36, v34, v35
	v_fma_f32 v37, -v33, v36, v34
	v_fmac_f32_e32 v36, v37, v35
	v_fma_f32 v33, -v33, v36, v34
	v_div_fmas_f32 v33, v33, v35, v36
	v_div_fixup_f32 v32, v33, v32, 1.0
	v_pk_mul_f32 v[0:1], v[0:1], v[32:33] op_sel_hi:[1,0]
	v_pk_mul_f32 v[2:3], v[2:3], v[32:33] op_sel_hi:[1,0]
	s_waitcnt vmcnt(0)
	v_pk_mul_f32 v[0:1], v[64:65], v[0:1]
	v_pk_mul_f32 v[2:3], v[66:67], v[2:3]
	v_cvt_pk_bf16_f32 v0, v0, v1
	v_pk_mul_f32 v[4:5], v[4:5], v[32:33] op_sel_hi:[1,0]
	v_cvt_pk_bf16_f32 v1, v2, v3
	global_store_dwordx2 v[100:101], v[0:1], off
	v_pk_mul_f32 v[6:7], v[6:7], v[32:33] op_sel_hi:[1,0]
	v_pk_mul_f32 v[0:1], v[176:177], v[4:5]
	v_pk_mul_f32 v[2:3], v[178:179], v[6:7]
	v_cvt_pk_bf16_f32 v0, v0, v1
	v_pk_mul_f32 v[4:5], v[8:9], v[32:33] op_sel_hi:[1,0]
	v_cvt_pk_bf16_f32 v1, v2, v3
	global_store_dwordx2 v[100:101], v[0:1], off offset:512
	v_pk_mul_f32 v[6:7], v[10:11], v[32:33] op_sel_hi:[1,0]
	v_pk_mul_f32 v[0:1], v[180:181], v[4:5]
	v_pk_mul_f32 v[2:3], v[182:183], v[6:7]
	v_cvt_pk_bf16_f32 v0, v0, v1
	v_pk_mul_f32 v[4:5], v[14:15], v[32:33] op_sel_hi:[1,0]
	v_cvt_pk_bf16_f32 v1, v2, v3
	global_store_dwordx2 v[100:101], v[0:1], off offset:1024
	v_pk_mul_f32 v[6:7], v[12:13], v[32:33] op_sel_hi:[1,0]
	v_pk_mul_f32 v[0:1], v[184:185], v[4:5]
	v_pk_mul_f32 v[2:3], v[186:187], v[6:7]
	v_cvt_pk_bf16_f32 v0, v0, v1
	v_pk_mul_f32 v[4:5], v[18:19], v[32:33] op_sel_hi:[1,0]
	v_cvt_pk_bf16_f32 v1, v2, v3
	global_store_dwordx2 v[100:101], v[0:1], off offset:1536
	v_pk_mul_f32 v[6:7], v[16:17], v[32:33] op_sel_hi:[1,0]
	v_pk_mul_f32 v[0:1], v[188:189], v[4:5]
	v_pk_mul_f32 v[2:3], v[190:191], v[6:7]
	v_cvt_pk_bf16_f32 v0, v0, v1
	v_pk_mul_f32 v[4:5], v[20:21], v[32:33] op_sel_hi:[1,0]
	v_cvt_pk_bf16_f32 v1, v2, v3
	global_store_dwordx2 v[100:101], v[0:1], off offset:2048
	v_pk_mul_f32 v[6:7], v[22:23], v[32:33] op_sel_hi:[1,0]
	v_pk_mul_f32 v[0:1], v[4:5], v[192:193]
	v_pk_mul_f32 v[2:3], v[6:7], v[194:195]
	v_cvt_pk_bf16_f32 v0, v0, v1
	v_pk_mul_f32 v[4:5], v[26:27], v[32:33] op_sel_hi:[1,0]
	v_cvt_pk_bf16_f32 v1, v2, v3
	global_store_dwordx2 v[100:101], v[0:1], off offset:2560
	v_pk_mul_f32 v[6:7], v[24:25], v[32:33] op_sel_hi:[1,0]
	v_pk_mul_f32 v[0:1], v[4:5], v[196:197]
	v_pk_mul_f32 v[2:3], v[6:7], v[198:199]
	v_cvt_pk_bf16_f32 v0, v0, v1
	v_pk_mul_f32 v[4:5], v[30:31], v[32:33] op_sel_hi:[1,0]
	v_cvt_pk_bf16_f32 v1, v2, v3
	global_store_dwordx2 v[100:101], v[0:1], off offset:3072
	v_pk_mul_f32 v[6:7], v[28:29], v[32:33] op_sel_hi:[1,0]
	v_pk_mul_f32 v[0:1], v[4:5], v[200:201]
	v_pk_mul_f32 v[2:3], v[6:7], v[202:203]
	v_cvt_pk_bf16_f32 v0, v0, v1
	s_nop 0
	v_cvt_pk_bf16_f32 v1, v2, v3
	global_store_dwordx2 v[100:101], v[0:1], off offset:3584
	s_cbranch_scc1 .LBB0_1091
